# GQA attention: V key rows loaded bit2/bit3-swapped so PV needs no permlane32_swap of P (same trick as differential attention)
# speedup vs baseline: 1.0099x; 1.0058x over previous
; __device__ __forceinline__ int v_st(int k, int c) { const int kk = (k & ~0xC) | ((k & 4) << 1) | ((k & 8) >> 1); return ((kk >> 3) * 4 + (c >> 5)) * 512 + ((kk & 7) * 32 + (c & 31)) * 2; }
; __device__ __forceinline__ int v_rd_base(int lane) { return ((lane & 3) << 3) | (((lane >> 2) & 3) << 6) | (((lane >> 4) & 1) << 5) | (((lane >> 5) & 1) << 8); }
; #define SLOAD(i, k0) do { sr_[i].vs0 = *reinterpret_cast<const bf16x8*>(&Vh[(long)((k0) + sr) * LDP + sc]); sr_[i].vs1 = *reinterpret_cast<const bf16x8*>(&Vh[(long)((k0) + 32 + sr) * LDP + sc]); \
;     sr_[i].ks0 = *reinterpret_cast<const bf16x8*>(&Kh[(long)((k0) + ksr) * LDP + ksc]); if (DK == 128) sr_[i].ks1 = *reinterpret_cast<const bf16x8*>(&Kh[(long)((k0) + 32 + ksr) * LDP + ksc]); } while (0)
; template <int DK, bool NA, bool QL, int SD> ...
;     ...
;   const bf16* Qw = Qb + (long)(wid * 32 + r32) * LDP + hi * 8;
; #pragma unroll
;   for (int d0 = 0; d0 < DK / 16; ++d0) { const bf16x8 qv = *reinterpret_cast<const bf16x8*>(Qw + d0 * 16); if (QL) *reinterpret_cast<bf16x8*>(ql + d0 * 1024) = qv; else qr[d0] = qv; }
;   const int sr = tid >> 4, sc = (tid & 15) * 8, vst0 = v_st(sr, sc), vst1 = v_st(32 + sr, sc);
;   const int ksr = DK == 128 ? sr : (tid >> 3), ksc = DK == 128 ? sc : (tid & 7) * 8;
;   const int vb0 = (int)(uintptr_t)V_lds + v_rd_base(lane);
;   struct { bf16x8 vs0, vs1, ks0, ks1; } sr_[SD];
;     ...
;   f32x16 pA0, pA1, pB0, pB1; float mnA, mnB, alA, alB; bf16x8 pa0, pa1, pa2, pa3;
;   constexpr int SE = 0, SO = SD - 1;
;   SLOAD(SE, 0); asm volatile("s_waitcnt vmcnt(0)" ::: "memory"); SWRITE(0, SE); __syncthreads();
.LBB0_658:
	s_and_b64 vcc, exec, s[0:1]
	s_cbranch_vccz .LBB0_679
	v_mov_b32_e32 v50, v188
	v_readlane_b32 s0, v253, 11
	v_readlane_b32 s1, v253, 12
	v_ashrrev_i32_e32 v53, 6, v50
	v_and_b32_e32 v51, 31, v50
	v_lshl_or_b32 v0, v53, 5, v51
	v_mov_b64_e32 v[2:3], s[0:1]
	s_movk_i32 s3, 0x2800
	v_mad_i64_i32 v[2:3], s[0:1], v0, s3, v[2:3]
	v_lshrrev_b32_e32 v0, 1, v50
	v_and_b32_e32 v0, 16, v0
	v_ashrrev_i32_e32 v52, 4, v50
	v_bfe_u32 v178, v52, 2, 1
	v_bfe_u32 v179, v52, 3, 1
	v_sub_u32_e32 v178, v178, v179
	v_mul_i32_i24_e32 v178, 0xa000, v178
	v_ashrrev_i32_e32 v179, 31, v178
	v_lshl_add_u64 v[30:31], v[2:3], 0, v[0:1]
	v_lshlrev_b32_e32 v54, 3, v50
	v_add_u32_e32 v55, 32, v52
	s_movk_i32 s9, 0x1400
	global_load_dwordx4 v[2:5], v[30:31], off
	global_load_dwordx4 v[6:9], v[30:31], off offset:32
	global_load_dwordx4 v[10:13], v[30:31], off offset:64
	global_load_dwordx4 v[14:17], v[30:31], off offset:96
	global_load_dwordx4 v[18:21], v[30:31], off offset:128
	global_load_dwordx4 v[22:25], v[30:31], off offset:160
	global_load_dwordx4 v[26:29], v[30:31], off offset:192
	s_nop 0
	global_load_dwordx4 v[30:33], v[30:31], off offset:224
	v_and_b32_e32 v71, 0x78, v54
	v_mad_i64_i32 v[34:35], s[0:1], v52, s9, 0
	v_mad_i64_i32 v[36:37], s[0:1], v55, s9, 0
	v_or_b32_e32 v34, v34, v71
	v_readlane_b32 s6, v253, 15
	v_or_b32_e32 v36, v36, v71
	v_readlane_b32 s4, v253, 13
	v_lshlrev_b64 v[42:43], 1, v[34:35]
	v_readlane_b32 s7, v253, 16
	v_lshlrev_b64 v[44:45], 1, v[36:37]
	v_readlane_b32 s5, v253, 14
	v_lshl_add_u64 v[34:35], s[6:7], 0, v[42:43]
	v_lshl_add_u64 v[34:35], v[34:35], 0, v[178:179]
	v_lshl_add_u64 v[38:39], s[6:7], 0, v[44:45]
	v_lshl_add_u64 v[38:39], v[38:39], 0, v[178:179]
	v_lshl_add_u64 v[42:43], s[4:5], 0, v[42:43]
	v_lshl_add_u64 v[46:47], s[4:5], 0, v[44:45]
	global_load_dwordx4 v[34:37], v[34:35], off
	s_nop 0
	global_load_dwordx4 v[38:41], v[38:39], off
	s_nop 0
	global_load_dwordx4 v[42:45], v[42:43], off
	s_nop 0
	global_load_dwordx4 v[46:49], v[46:47], off
	v_and_b32_e32 v72, 63, v50
	v_readlane_b32 s0, v254, 57
	v_lshlrev_b32_e32 v57, 4, v72
	v_and_b32_e32 v58, 0xfffff0, v52
	v_lshl_add_u32 v53, v53, 13, s0
	v_lshlrev_b32_e32 v59, 1, v52
	v_lshrrev_b32_e32 v60, 1, v52
	v_and_b32_e32 v61, 3, v52
	v_add_u32_e32 v153, v53, v57
	v_and_or_b32 v53, v59, 8, v58
	v_and_or_b32 v58, v60, 4, v61
	v_and_b32_e32 v60, 0xfffff0, v55
	v_lshlrev_b32_e32 v61, 1, v55
	v_and_b32_e32 v56, 0xf0, v50
	v_bfe_u32 v54, v54, 5, 2
	v_lshlrev_b32_e32 v62, 8, v52
	v_lshlrev_b32_e32 v59, 1, v71
	v_lshlrev_b32_e32 v55, 8, v55
	v_lshrrev_b32_e32 v53, 1, v53
	v_and_or_b32 v60, v61, 8, v60
	v_bitop3_b32 v61, v59, v62, v56 bitop3:0xde
	v_bitop3_b32 v55, v59, v55, v56 bitop3:0xde
	v_or_b32_e32 v53, v53, v54
	v_lshrrev_b32_e32 v56, 1, v60
	v_lshlrev_b32_e32 v58, 6, v58
	v_and_b32_e32 v63, 48, v59
	v_lshlrev_b32_e32 v53, 9, v53
	v_or_b32_e32 v54, v56, v54
	v_or3_b32 v53, v53, v58, v63
	v_lshlrev_b32_e32 v54, 9, v54
	v_or3_b32 v54, v54, v58, v63
	v_add_u32_e32 v209, 0, v53
	v_lshlrev_b32_e32 v53, 8, v51
	v_add_u32_e32 v177, 0, v61
	v_add_u32_e32 v208, 0, v55
	v_add_u32_e32 v210, 0, v54
	v_and_b32_e32 v54, 0x3fffffc0, v50
	s_add_i32 s0, 0, 0x10000
	v_lshl_add_u32 v148, v54, 2, s0
	v_readlane_b32 s12, v254, 62
	s_cmp_lg_u32 0, -1
	v_readlane_b32 s13, v254, 63
	v_readlane_b32 s14, v255, 0
	v_readlane_b32 s15, v255, 1
	s_mov_b32 s8, -1
	s_cselect_b32 s2, 0, 0
	v_readlane_b32 s16, v255, 2
	v_readlane_b32 s17, v255, 3
	s_waitcnt vmcnt(11)
	ds_write_b128 v153, v[2:5]
	s_waitcnt vmcnt(10)
	ds_write_b128 v153, v[6:9] offset:1024
	s_waitcnt vmcnt(9)
	ds_write_b128 v153, v[10:13] offset:2048
	s_waitcnt vmcnt(8)
	ds_write_b128 v153, v[14:17] offset:3072
	s_waitcnt vmcnt(7)
	ds_write_b128 v153, v[18:21] offset:4096
	s_waitcnt vmcnt(6)
	ds_write_b128 v153, v[22:25] offset:5120
	s_waitcnt vmcnt(5)
	ds_write_b128 v153, v[26:29] offset:6144
	s_waitcnt vmcnt(4)
	ds_write_b128 v153, v[30:33] offset:7168
	v_lshlrev_b32_e32 v2, 4, v50
	v_and_b32_e32 v58, 0xf0, v2
	v_bitop3_b32 v2, v0, v53, v58 bitop3:0xde
	v_add_u32_e32 v159, 0, v2
	s_waitcnt vmcnt(0)
	s_waitcnt vmcnt(3)
	ds_write_b128 v209, v[34:37]
	s_waitcnt vmcnt(2)
	ds_write_b128 v210, v[38:41]
	s_waitcnt vmcnt(1)
	ds_write_b128 v177, v[42:45] offset:32768
	s_waitcnt vmcnt(0)
	ds_write_b128 v208, v[46:49] offset:32768
	s_waitcnt lgkmcnt(0)
	s_barrier
; __device__ __forceinline__ void partialSM(f32x16& p0, f32x16& p1, float& m_reg, float& mn, float& alpha, float C, float thrRaw) {
;   float pmax = p0[0];
; #pragma unroll
;   for (int r = 1; r < 16; ++r) pmax = fmaxf(pmax, p0[r]);
; #pragma unroll
;   for (int r = 0; r < 16; ++r) pmax = fmaxf(pmax, p1[r]);
;   { auto rr = __builtin_amdgcn_permlane32_swap(__float_as_uint(pmax), __float_as_uint(pmax), false, false);
;     pmax = fmaxf(__uint_as_float(rr[0]), __uint_as_float(rr[1])); }
;   if (__builtin_expect(__all(pmax - m_reg <= thrRaw), 1)) { mn = m_reg; alpha = 1.f; }
;   else { mn = fmaxf(m_reg, pmax); alpha = __builtin_amdgcn_exp2f((m_reg - mn) * C); m_reg = mn; }
; template <int DK, bool QL>
; __device__ __forceinline__ void qkt(f32x16& p0, f32x16& p1, const bf16* Ks, const bf16x8* qr, const char* ql, int r32, int hi) {
;   p0 = f32x16{}; p1 = f32x16{};
; #pragma unroll
;   for (int d0 = 0; d0 < DK / 16; ++d0) { int cb = (d0 * 16 + hi * 8) * 2;
;     const bf16x8 qv = QL ? *reinterpret_cast<const bf16x8*>(ql + d0 * 1024) : qr[d0];
;     bf16x8 b0 = *reinterpret_cast<const bf16x8*>((const char*)Ks + kswz<DK>(r32, cb));
;     bf16x8 b1 = *reinterpret_cast<const bf16x8*>((const char*)Ks + kswz<DK>(32 + r32, cb));
;     p0 = __builtin_amdgcn_mfma_f32_32x32x16_bf16(b0, qv, p0, 0, 0, 0);
;     p1 = __builtin_amdgcn_mfma_f32_32x32x16_bf16(b1, qv, p1, 0, 0, 0); }
; }
	ds_read_b128 v[2:5], v159 offset:32768
	ds_read_b128 v[6:9], v153
	ds_read_b128 v[10:13], v159 offset:40960
	ds_read_b128 v[14:17], v153 offset:1024
	s_waitcnt lgkmcnt(2)
	v_mfma_f32_32x32x16_bf16 v[34:49], v[2:5], v[6:9], 0
	v_or_b32_e32 v2, 32, v0
	v_bitop3_b32 v2, v2, v53, v58 bitop3:0xde
	v_add_u32_e32 v207, 0, v2
	v_readlane_b32 s18, v255, 4
	v_readlane_b32 s19, v255, 5
	v_readlane_b32 s20, v255, 6
	v_readlane_b32 s21, v255, 7
	s_waitcnt lgkmcnt(1)
	v_mfma_f32_32x32x16_bf16 v[18:33], v[10:13], v[6:9], 0
	ds_read_b128 v[2:5], v207 offset:32768
	ds_read_b128 v[6:9], v207 offset:40960
	v_readlane_b32 s22, v255, 8
	v_readlane_b32 s23, v255, 9
	v_readlane_b32 s24, v255, 10
	v_readlane_b32 s25, v255, 11
	v_readlane_b32 s26, v255, 12
	v_readlane_b32 s27, v255, 13
	s_waitcnt lgkmcnt(1)
	v_mfma_f32_32x32x16_bf16 v[34:49], v[2:5], v[14:17], v[34:49]
	v_or_b32_e32 v2, 64, v0
	v_bitop3_b32 v2, v2, v53, v58 bitop3:0xde
	v_add_u32_e32 v161, 0, v2
	s_mov_b32 s12, s13
	s_mov_b32 s14, s13
	s_mov_b32 s15, s13
	s_mov_b32 s1, s13
	s_waitcnt lgkmcnt(0)
	v_mfma_f32_32x32x16_bf16 v[18:33], v[6:9], v[14:17], v[18:33]
	ds_read_b128 v[2:5], v161 offset:32768
	ds_read_b128 v[6:9], v153 offset:2048
	ds_read_b128 v[10:13], v161 offset:40960
	ds_read_b128 v[14:17], v153 offset:3072
	s_mov_b32 s16, s13
	s_mov_b32 s17, s13
	s_mov_b32 s18, s13
	s_mov_b32 s19, s13
	s_mov_b32 s20, s13
	s_mov_b32 s21, s13
	s_waitcnt lgkmcnt(2)
	v_mfma_f32_32x32x16_bf16 v[34:49], v[2:5], v[6:9], v[34:49]
	v_or_b32_e32 v2, 0x60, v0
	v_bitop3_b32 v2, v2, v53, v58 bitop3:0xde
	v_add_u32_e32 v160, 0, v2
	s_mov_b32 s22, s13
	s_mov_b32 s23, s13
	s_mov_b32 s24, s13
	s_mov_b32 s25, s13
	s_waitcnt lgkmcnt(1)
	v_mfma_f32_32x32x16_bf16 v[18:33], v[10:13], v[6:9], v[18:33]
	ds_read_b128 v[2:5], v160 offset:32768
	ds_read_b128 v[6:9], v160 offset:40960
	s_mov_b32 s26, s13
	s_mov_b32 s27, s13
	v_mov_b32_e32 v150, 0
	v_lshl_add_u32 v149, v51, 2, v148
	v_mov_b32_e32 v51, v150
	s_waitcnt lgkmcnt(1)
	v_mfma_f32_32x32x16_bf16 v[34:49], v[2:5], v[14:17], v[34:49]
	v_or_b32_e32 v2, 0x80, v0
	v_bitop3_b32 v2, v2, v53, v58 bitop3:0xde
	v_add_u32_e32 v158, 0, v2
	s_waitcnt lgkmcnt(0)
	v_mfma_f32_32x32x16_bf16 v[18:33], v[6:9], v[14:17], v[18:33]
	ds_read_b128 v[2:5], v158 offset:32768
	ds_read_b128 v[6:9], v153 offset:4096
	ds_read_b128 v[10:13], v158 offset:40960
	ds_read_b128 v[14:17], v153 offset:5120
	s_waitcnt lgkmcnt(2)
	v_mfma_f32_32x32x16_bf16 v[34:49], v[2:5], v[6:9], v[34:49]
	v_or_b32_e32 v2, 0xa0, v0
	v_bitop3_b32 v2, v2, v53, v58 bitop3:0xde
	v_add_u32_e32 v156, 0, v2
	ds_read_b128 v[2:5], v156 offset:32768
	s_waitcnt lgkmcnt(2)
	v_mfma_f32_32x32x16_bf16 v[18:33], v[10:13], v[6:9], v[18:33]
	v_lshlrev_b32_e32 v10, 3, v72
	v_and_b32_e32 v6, 0xc0, v57
	v_and_or_b32 v11, v10, 24, v6
	ds_read_b128 v[6:9], v156 offset:40960
	v_lshlrev_b32_e32 v12, 1, v50
	s_waitcnt lgkmcnt(0)
	v_mfma_f32_32x32x16_bf16 v[18:33], v[6:9], v[14:17], v[18:33]
	ds_read_b128 v[6:9], v153 offset:6144
	v_mfma_f32_32x32x16_bf16 v[34:49], v[2:5], v[14:17], v[34:49]
	v_and_b32_e32 v2, 32, v12
	v_and_b32_e32 v3, 0x100, v10
	v_or3_b32 v73, v11, v2, v3
	v_or_b32_e32 v2, 0xc0, v0
	v_bitop3_b32 v2, v2, v53, v58 bitop3:0xde
	v_add_u32_e32 v157, 0, v2
	ds_read_b128 v[2:5], v157 offset:32768
	s_waitcnt lgkmcnt(0)
	v_mfma_f32_32x32x16_bf16 v[34:49], v[2:5], v[6:9], v[34:49]
	v_or_b32_e32 v2, 0xe0, v0
	v_bitop3_b32 v2, v2, v53, v58 bitop3:0xde
	v_add_u32_e32 v176, 0, v2
	ds_read_b128 v[10:13], v157 offset:40960
	ds_read_b128 v[54:57], v153 offset:7168
	ds_read_b128 v[2:5], v176 offset:32768
	ds_read_b128 v[58:61], v176 offset:40960
	v_add_u32_e32 v152, s2, v73
	s_waitcnt lgkmcnt(3)
	v_mfma_f32_32x32x16_bf16 v[18:33], v[10:13], v[6:9], v[18:33]
	v_writelane_b32 v254, s0, 62
	s_nop 1
	v_writelane_b32 v255, s2, 0
	v_writelane_b32 v255, s3, 1
	v_writelane_b32 v255, s4, 2
	v_writelane_b32 v255, s5, 3
	s_waitcnt lgkmcnt(1)
	v_mfma_f32_32x32x16_bf16 v[34:49], v[2:5], v[54:57], v[34:49]
	v_writelane_b32 v255, s6, 4
	v_writelane_b32 v255, s7, 5
	v_writelane_b32 v255, s8, 6
	v_writelane_b32 v255, s9, 7
	v_writelane_b32 v255, s10, 8
	v_writelane_b32 v255, s11, 9
	v_writelane_b32 v255, s12, 10
	s_waitcnt lgkmcnt(0)
	v_mfma_f32_32x32x16_bf16 v[18:33], v[58:61], v[54:57], v[18:33]
	s_nop 2
	v_max_f32_e32 v53, v35, v35
	v_max_f32_e32 v54, v34, v34
	v_max_f32_e32 v53, v54, v53
	v_max3_f32 v53, v53, v36, v37
	v_max3_f32 v53, v53, v38, v39
	v_max3_f32 v53, v53, v40, v41
	v_max3_f32 v53, v53, v42, v43
	v_max3_f32 v53, v53, v44, v45
	v_max3_f32 v53, v53, v46, v47
	v_max3_f32 v53, v53, v48, v49
	v_max3_f32 v53, v53, v18, v19
	v_max3_f32 v53, v53, v20, v21
	v_max3_f32 v53, v53, v22, v23
	v_max3_f32 v53, v53, v24, v25
	v_max3_f32 v53, v53, v26, v27
	v_max3_f32 v53, v53, v28, v29
	v_max3_f32 v53, v53, v30, v31
	v_max3_f32 v53, v53, v32, v33
	v_mov_b32_e32 v70, v53
	v_writelane_b32 v255, s13, 11
	s_nop 0
	v_permlane32_swap_b32_e32 v53, v70
	v_writelane_b32 v255, s14, 12
	v_add_u32_e32 v54, 64, v52
	v_add_u32_e32 v56, 0x60, v52
	v_max_f32_e32 v70, v70, v70
	v_max_f32_e32 v53, v53, v53
	v_writelane_b32 v254, s1, 63
	v_writelane_b32 v255, s15, 13
	v_mad_i64_i32 v[54:55], s[0:1], v54, s9, 0
	v_mad_i64_i32 v[56:57], s[0:1], v56, s9, 0
	v_max_f32_e32 v53, v53, v70
	v_add_f32_e32 v70, 0x7149f2ca, v53
	s_mov_b32 s0, 0x42b504f3
	v_max_f32_e32 v53, 0xf149f2ca, v53
	v_cmp_ge_f32_e32 vcc, s0, v70
	v_sub_f32_e32 v70, 0xf149f2ca, v53
	v_mul_f32_e32 v70, 0x3e0293ee, v70
	v_exp_f32_e32 v70, v70
	s_cmp_eq_u64 vcc, exec
	s_cselect_b64 vcc, -1, 0
	v_cndmask_b32_e32 v134, v53, v199, vcc
	v_cndmask_b32_e64 v211, v70, 1.0, vcc
	v_mul_f32_e32 v70, 0xbe0293ee, v134
; #define SLOAD(i, k0) do { sr_[i].vs0 = *reinterpret_cast<const bf16x8*>(&Vh[(long)((k0) + sr) * LDP + sc]); sr_[i].vs1 = *reinterpret_cast<const bf16x8*>(&Vh[(long)((k0) + 32 + sr) * LDP + sc]); \
;     sr_[i].ks0 = *reinterpret_cast<const bf16x8*>(&Kh[(long)((k0) + ksr) * LDP + ksc]); if (DK == 128) sr_[i].ks1 = *reinterpret_cast<const bf16x8*>(&Kh[(long)((k0) + 32 + ksr) * LDP + ksc]); } while (0)
; #define SWAIT() do { if (SD == 1) asm volatile("s_waitcnt vmcnt(0)" ::: "memory"); else if (DK == 128) asm volatile("s_waitcnt vmcnt(4)" ::: "memory"); else asm volatile("s_waitcnt vmcnt(3)" ::: "memory"); } while (0)
; #define HOOK(P0, P1, j) do { if (NA) na_hook(P0, P1, krow0 + (j), q_row, q_col, win_r, win_c, rpb, inv_scale, hi); } while (0)
; __device__ __forceinline__ void partialSM(f32x16& p0, f32x16& p1, float& m_reg, float& mn, float& alpha, float C, float thrRaw) {
;     ...
;   for (int r = 0; r < 16; ++r) p0[r] = fmaf(p0[r], C, mnC);
; #pragma unroll
;   for (int r = 0; r < 16; ++r) p1[r] = fmaf(p1[r], C, mnC);
; #pragma unroll
;   for (int r = 0; r < 16; ++r) p0[r] = __builtin_amdgcn_exp2f(p0[r]);
; template <int DK, bool NA, bool QL, int SD> ...
;     ...
;   f32x16 pA0, pA1, pB0, pB1; float mnA, mnB, alA, alB; bf16x8 pa0, pa1, pa2, pa3;
;   constexpr int SE = 0, SO = SD - 1;
;   SLOAD(SE, 0); asm volatile("s_waitcnt vmcnt(0)" ::: "memory"); SWRITE(0, SE); __syncthreads();
;   qkt<DK, QL>(pA0, pA1, K_lds, qr, ql, r32, hi); HOOK(pA0, pA1, 0); partialSM(pA0, pA1, m_reg, mnA, alA, C, thrRaw);
;   SLOAD(SO, KVBLK); if (SD == 2) { if (2 < NT) SLOAD(SE, 2 * KVBLK); }
;   SWAIT(); SWRITE(1, SO); __syncthreads();
	v_fmamk_f32 v53, v34, 0x3e0293ee, v70
	v_add_u32_e32 v34, 0xa0, v52
	v_or_b32_e32 v54, v54, v71
	v_or_b32_e32 v56, v56, v71
	v_fmamk_f32 v74, v35, 0x3e0293ee, v70
	v_fmamk_f32 v77, v38, 0x3e0293ee, v70
	v_mad_i64_i32 v[34:35], s[0:1], v34, s9, 0
	v_add_u32_e32 v38, 0x80, v52
	v_lshlrev_b64 v[62:63], 1, v[54:55]
	v_lshlrev_b64 v[64:65], 1, v[56:57]
	v_fmamk_f32 v78, v39, 0x3e0293ee, v70
	v_or_b32_e32 v34, v34, v71
	v_mad_i64_i32 v[38:39], s[0:1], v38, s9, 0
	v_lshl_add_u64 v[54:55], s[6:7], 0, v[62:63]
	v_lshl_add_u64 v[54:55], v[54:55], 0, v[178:179]
	v_lshl_add_u64 v[58:59], s[6:7], 0, v[64:65]
	v_lshl_add_u64 v[58:59], v[58:59], 0, v[178:179]
	v_lshl_add_u64 v[62:63], s[4:5], 0, v[62:63]
	v_lshl_add_u64 v[66:67], s[4:5], 0, v[64:65]
	v_lshlrev_b64 v[34:35], 1, v[34:35]
	v_or_b32_e32 v38, v38, v71
	global_load_dwordx4 v[54:57], v[54:55], off
	s_nop 0
	global_load_dwordx4 v[58:61], v[58:59], off
	s_nop 0
	global_load_dwordx4 v[62:65], v[62:63], off
	s_nop 0
	global_load_dwordx4 v[66:69], v[66:67], off
	v_fmamk_f32 v75, v36, 0x3e0293ee, v70
	v_fmamk_f32 v76, v37, 0x3e0293ee, v70
	v_lshl_add_u64 v[36:37], s[4:5], 0, v[34:35]
	v_lshlrev_b64 v[38:39], 1, v[38:39]
	v_lshl_add_u64 v[34:35], s[6:7], 0, v[34:35]
	v_lshl_add_u64 v[34:35], v[34:35], 0, v[178:179]
	v_fmamk_f32 v79, v40, 0x3e0293ee, v70
	v_fmamk_f32 v80, v41, 0x3e0293ee, v70
	v_lshl_add_u64 v[40:41], s[4:5], 0, v[38:39]
	global_load_dwordx4 v[102:105], v[36:37], off
	global_load_dwordx4 v[98:101], v[40:41], off
	v_lshl_add_u64 v[36:37], s[6:7], 0, v[38:39]
	v_lshl_add_u64 v[36:37], v[36:37], 0, v[178:179]
	global_load_dwordx4 v[110:113], v[34:35], off
	global_load_dwordx4 v[106:109], v[36:37], off
	v_mov_b32_e32 v36, v70
	s_mov_b32 s0, 0x3e0293ee
	s_addk_i32 s2, 0x4000
	v_fmamk_f32 v42, v42, 0x3e0293ee, v70
	v_fmamk_f32 v43, v43, 0x3e0293ee, v70
	v_fmamk_f32 v44, v44, 0x3e0293ee, v70
	v_fmamk_f32 v45, v45, 0x3e0293ee, v70
	v_fmamk_f32 v46, v46, 0x3e0293ee, v70
	v_fmamk_f32 v34, v47, 0x3e0293ee, v70
	v_fmamk_f32 v35, v48, 0x3e0293ee, v70
	v_fmac_f32_e32 v36, 0x3e0293ee, v49
	v_pk_fma_f32 v[126:127], v[18:19], s[0:1], v[70:71] op_sel_hi:[1,0,0]
	v_add_u32_e32 v151, s2, v73
	v_mad_i64_i32 v[18:19], s[2:3], v52, s3, 0
	v_mov_b64_e32 v[2:3], s[12:13]
	v_pk_fma_f32 v[124:125], v[20:21], s[0:1], v[70:71] op_sel_hi:[1,0,0]
	v_exp_f32_e32 v145, v53
	v_exp_f32_e32 v216, v74
	v_exp_f32_e32 v131, v75
	v_exp_f32_e32 v215, v76
	v_exp_f32_e32 v132, v77
	v_exp_f32_e32 v144, v78
	v_exp_f32_e32 v133, v79
	v_exp_f32_e32 v143, v80
	v_exp_f32_e32 v140, v42
	v_exp_f32_e32 v142, v43
	v_exp_f32_e32 v139, v44
	v_exp_f32_e32 v141, v45
	v_exp_f32_e32 v136, v46
	v_exp_f32_e32 v138, v34
	v_exp_f32_e32 v135, v35
	v_exp_f32_e32 v137, v36
	v_and_b32_e32 v20, 15, v50
	v_readlane_b32 s2, v254, 30
	v_mov_b64_e32 v[16:17], s[26:27]
	s_waitcnt vmcnt(4)
	v_lshl_or_b32 v18, v20, 4, v18
	v_readlane_b32 s3, v254, 31
	v_mov_b64_e32 v[4:5], s[14:15]
	v_mov_b64_e32 v[6:7], s[16:17]
	v_mov_b64_e32 v[8:9], s[18:19]
	v_mov_b64_e32 v[10:11], s[20:21]
	v_mov_b64_e32 v[12:13], s[22:23]
	v_mov_b64_e32 v[14:15], s[24:25]
	v_pk_fma_f32 v[120:121], v[32:33], s[0:1], v[70:71] op_sel_hi:[1,0,0]
	v_pk_fma_f32 v[122:123], v[30:31], s[0:1], v[70:71] op_sel_hi:[1,0,0]
	v_pk_fma_f32 v[128:129], v[28:29], s[0:1], v[70:71] op_sel_hi:[1,0,0]
	v_pk_fma_f32 v[114:115], v[26:27], s[0:1], v[70:71] op_sel_hi:[1,0,0]
	v_pk_fma_f32 v[116:117], v[24:25], s[0:1], v[70:71] op_sel_hi:[1,0,0]
	v_pk_fma_f32 v[118:119], v[22:23], s[0:1], v[70:71] op_sel_hi:[1,0,0]
	v_lshl_add_u64 v[146:147], s[2:3], 0, v[18:19]
	v_mov_b64_e32 v[32:33], v[16:17]
	s_waitcnt vmcnt(7)
	ds_write_b128 v209, v[54:57] offset:16384
	s_waitcnt vmcnt(6)
	ds_write_b128 v210, v[58:61] offset:16384
	s_waitcnt vmcnt(5)
	ds_write_b128 v177, v[62:65] offset:49152
	s_waitcnt vmcnt(4)
	ds_write_b128 v208, v[66:69] offset:49152
	v_cmp_gt_u32_e64 s[0:1], 32, v72
	v_mov_b64_e32 v[30:31], v[14:15]
	v_mov_b64_e32 v[28:29], v[12:13]
	v_mov_b64_e32 v[26:27], v[10:11]
	v_mov_b64_e32 v[24:25], v[8:9]
	v_mov_b64_e32 v[22:23], v[6:7]
	v_mov_b64_e32 v[20:21], v[4:5]
	v_mov_b64_e32 v[18:19], v[2:3]
	v_mov_b32_e32 v34, 0
	v_mov_b32_e32 v35, v150
	v_mov_b32_e32 v36, v150
	v_mov_b32_e32 v37, v150
	v_mov_b32_e32 v38, v150
	v_mov_b32_e32 v39, v150
	v_mov_b32_e32 v40, v150
	v_mov_b32_e32 v41, v150
	v_mov_b32_e32 v42, v150
	v_mov_b32_e32 v43, v150
	v_mov_b32_e32 v44, v150
	v_mov_b32_e32 v45, v150
	v_mov_b32_e32 v46, v150
	v_mov_b32_e32 v47, v150
	v_mov_b32_e32 v48, v150
	v_mov_b32_e32 v49, v150
	v_mov_b32_e32 v50, 0
	v_mov_b32_e32 v52, v150
	v_mov_b32_e32 v53, v150
	v_mov_b32_e32 v54, v150
	v_mov_b32_e32 v55, v150
	v_mov_b32_e32 v56, v150
	v_mov_b32_e32 v57, v150
	v_mov_b32_e32 v58, v150
	v_mov_b32_e32 v59, v150
	v_mov_b32_e32 v60, v150
	v_mov_b32_e32 v61, v150
	v_mov_b32_e32 v62, v150
	v_mov_b32_e32 v63, v150
	v_mov_b32_e32 v64, v150
	v_mov_b32_e32 v65, v150
	s_waitcnt lgkmcnt(0)
	s_barrier
; #define SBAR() __builtin_amdgcn_sched_barrier(0)
; #define SLOAD(i, k0) do { sr_[i].vs0 = *reinterpret_cast<const bf16x8*>(&Vh[(long)((k0) + sr) * LDP + sc]); sr_[i].vs1 = *reinterpret_cast<const bf16x8*>(&Vh[(long)((k0) + 32 + sr) * LDP + sc]); \
;     sr_[i].ks0 = *reinterpret_cast<const bf16x8*>(&Kh[(long)((k0) + ksr) * LDP + ksc]); if (DK == 128) sr_[i].ks1 = *reinterpret_cast<const bf16x8*>(&Kh[(long)((k0) + 32 + ksr) * LDP + ksc]); } while (0)
; #define HOOK(P0, P1, j) do { if (NA) na_hook(P0, P1, krow0 + (j), q_row, q_col, win_r, win_c, rpb, inv_scale, hi); } while (0)
; __device__ __forceinline__ void finishSM(f32x16& p0, f32x16& p1, float alpha, float& l_reg, bf16x8& pa0, bf16x8& pa1, bf16x8& pa2, bf16x8& pa3) {
; #pragma unroll
;   for (int r = 0; r < 16; ++r) p1[r] = __builtin_amdgcn_exp2f(p1[r]);
;   float ps = 0;
; #pragma unroll
;   for (int r = 0; r < 16; ++r) ps += p0[r];
; #pragma unroll
;   for (int r = 0; r < 16; ++r) ps += p1[r];
;   { auto rr = __builtin_amdgcn_permlane32_swap(__float_as_uint(ps), __float_as_uint(ps), false, false);
;     ps = __uint_as_float(rr[0]) + __uint_as_float(rr[1]); }
;   l_reg = l_reg * alpha + ps;
;     ...
;   PK4(p0, 0, pa0); PK4(p0, 8, pa1); PK4(p1, 0, pa2); PK4(p1, 8, pa3);
; template <int DK, bool NA, bool QL, int SD> ...
;     ...
;   for (int j = 1; j + 1 < NT; j += 2) {
;     SBAR(); qkt<DK, QL>(pB0, pB1, (bf16*)((char*)K_lds + SHM_K), qr, ql, r32, hi); HOOK(pB0, pB1, j);
;     finishSM(pA0, pA1, alA, l_reg, pa0, pa1, pa2, pa3); SBAR();
;     SLOAD(SO, (j + SD) * KVBLK); SBAR();
;     pv_d0(o, vb0, pa0, pa1, pa2, pa3); partialSM(pB0, pB1, m_reg, mnB, alB, C, thrRaw);
.LBB0_660:
	ds_read_b128 v[66:69], v153
	ds_read_b128 v[70:73], v159 offset:49152
	ds_read_b128 v[74:77], v159 offset:57344
	ds_read_b128 v[218:221], v153 offset:1024
	ds_read_b128 v[222:225], v207 offset:49152
	ds_read_b128 v[226:229], v207 offset:57344
	v_add_f32_e32 v130, v216, v145
	s_waitcnt lgkmcnt(4)
	v_mfma_f32_32x32x16_bf16 v[82:97], v[70:73], v[66:69], 0
	v_add_f32_e32 v130, v131, v130
	v_add_f32_e32 v130, v215, v130
	v_add_f32_e32 v130, v132, v130
	v_add_f32_e32 v130, v144, v130
	v_add_f32_e32 v130, v133, v130
	v_add_f32_e32 v130, v143, v130
	v_add_f32_e32 v130, v140, v130
	s_waitcnt lgkmcnt(3)
	v_mfma_f32_32x32x16_bf16 v[66:81], v[74:77], v[66:69], 0
	v_add_f32_e32 v130, v142, v130
	v_add_f32_e32 v130, v139, v130
	v_add_f32_e32 v130, v141, v130
	v_exp_f32_e32 v126, v126
	v_add_f32_e32 v130, v136, v130
	v_exp_f32_e32 v127, v127
	v_add_f32_e32 v130, v138, v130
	s_waitcnt lgkmcnt(1)
	v_mfma_f32_32x32x16_bf16 v[82:97], v[222:225], v[218:221], v[82:97]
	v_exp_f32_e32 v124, v124
	v_add_f32_e32 v130, v135, v130
	v_exp_f32_e32 v125, v125
	v_add_f32_e32 v130, v137, v130
	v_exp_f32_e32 v118, v118
	v_add_f32_e32 v130, v126, v130
	v_exp_f32_e32 v119, v119
	s_waitcnt lgkmcnt(0)
	v_mfma_f32_32x32x16_bf16 v[66:81], v[226:229], v[218:221], v[66:81]
	ds_read_b128 v[218:221], v153 offset:2048
	ds_read_b128 v[222:225], v161 offset:49152
	ds_read_b128 v[226:229], v161 offset:57344
	v_add_f32_e32 v130, v127, v130
	v_exp_f32_e32 v116, v116
	v_add_f32_e32 v130, v124, v130
	v_exp_f32_e32 v117, v117
	v_add_f32_e32 v130, v125, v130
	v_exp_f32_e32 v114, v114
	s_waitcnt lgkmcnt(1)
	v_mfma_f32_32x32x16_bf16 v[82:97], v[222:225], v[218:221], v[82:97]
	v_add_f32_e32 v130, v118, v130
	v_exp_f32_e32 v115, v115
	v_add_f32_e32 v130, v119, v130
	v_exp_f32_e32 v128, v128
	v_add_f32_e32 v130, v116, v130
	v_exp_f32_e32 v129, v129
	v_add_f32_e32 v130, v117, v130
	s_waitcnt lgkmcnt(0)
	v_mfma_f32_32x32x16_bf16 v[66:81], v[226:229], v[218:221], v[66:81]
	ds_read_b128 v[218:221], v153 offset:3072
	ds_read_b128 v[222:225], v160 offset:49152
	ds_read_b128 v[226:229], v160 offset:57344
	v_exp_f32_e32 v122, v122
	v_add_f32_e32 v130, v114, v130
	v_exp_f32_e32 v123, v123
	v_add_f32_e32 v130, v115, v130
	v_exp_f32_e32 v120, v120
	v_add_f32_e32 v130, v128, v130
	s_waitcnt lgkmcnt(1)
	v_mfma_f32_32x32x16_bf16 v[82:97], v[222:225], v[218:221], v[82:97]
	v_exp_f32_e32 v121, v121
	v_add_f32_e32 v130, v129, v130
	v_add_f32_e32 v130, v122, v130
	v_add_f32_e32 v130, v123, v130
	v_add_f32_e32 v130, v120, v130
	v_add_f32_e32 v212, v121, v130
	v_mov_b32_e32 v213, v212
	s_waitcnt lgkmcnt(0)
	v_mfma_f32_32x32x16_bf16 v[66:81], v[226:229], v[218:221], v[66:81]
	ds_read_b128 v[218:221], v153 offset:4096
	ds_read_b128 v[222:225], v158 offset:49152
	ds_read_b128 v[226:229], v158 offset:57344
	v_permlane32_swap_b32_e32 v212, v213
	s_waitcnt lgkmcnt(1)
	v_mfma_f32_32x32x16_bf16 v[82:97], v[222:225], v[218:221], v[82:97]
	s_waitcnt lgkmcnt(0)
	v_mfma_f32_32x32x16_bf16 v[66:81], v[226:229], v[218:221], v[66:81]
	ds_read_b128 v[218:221], v153 offset:5120
	ds_read_b128 v[222:225], v156 offset:49152
	ds_read_b128 v[226:229], v156 offset:57344
	s_waitcnt lgkmcnt(1)
	v_mfma_f32_32x32x16_bf16 v[82:97], v[222:225], v[218:221], v[82:97]
	s_waitcnt lgkmcnt(0)
	v_mfma_f32_32x32x16_bf16 v[66:81], v[226:229], v[218:221], v[66:81]
	ds_read_b128 v[218:221], v153 offset:6144
	ds_read_b128 v[222:225], v157 offset:49152
	ds_read_b128 v[226:229], v157 offset:57344
	s_waitcnt lgkmcnt(1)
	v_mfma_f32_32x32x16_bf16 v[82:97], v[222:225], v[218:221], v[82:97]
	s_waitcnt lgkmcnt(0)
	v_mfma_f32_32x32x16_bf16 v[66:81], v[226:229], v[218:221], v[66:81]
	ds_read_b128 v[218:221], v153 offset:7168
	ds_read_b128 v[222:225], v176 offset:49152
	ds_read_b128 v[226:229], v176 offset:57344
	v_cvt_pk_bf16_f32 v130, v145, v216
	v_cvt_pk_bf16_f32 v131, v131, v215
	v_cvt_pk_bf16_f32 v132, v132, v144
	v_cvt_pk_bf16_f32 v133, v133, v143
	v_cvt_pk_bf16_f32 v140, v140, v142
	v_cvt_pk_bf16_f32 v141, v139, v141
	s_waitcnt lgkmcnt(1)
	v_mfma_f32_32x32x16_bf16 v[82:97], v[222:225], v[218:221], v[82:97]
	v_cvt_pk_bf16_f32 v142, v136, v138
	v_cvt_pk_bf16_f32 v143, v135, v137
	v_cvt_pk_bf16_f32 v136, v126, v127
	v_cvt_pk_bf16_f32 v137, v124, v125
	v_cvt_pk_bf16_f32 v138, v118, v119
	v_cvt_pk_bf16_f32 v139, v116, v117
	v_cvt_pk_bf16_f32 v214, v114, v115
	s_waitcnt lgkmcnt(0)
	v_mfma_f32_32x32x16_bf16 v[66:81], v[226:229], v[218:221], v[66:81]
	v_cvt_pk_bf16_f32 v215, v128, v129
	v_cvt_pk_bf16_f32 v216, v122, v123
	v_cvt_pk_bf16_f32 v217, v120, v121
	s_mov_b32 s2, 0xfff10000
	v_add_co_u32_e32 v118, vcc, s2, v146
	s_mov_b32 s2, 0xfff60000
	s_nop 0
	v_addc_co_u32_e32 v119, vcc, -1, v147, vcc
	v_add_co_u32_e32 v122, vcc, s2, v146
	s_nop 1
	v_addc_co_u32_e32 v123, vcc, -1, v147, vcc
	v_lshl_add_u64 v[164:165], v[118:119], 0, v[178:179]
	global_load_dwordx4 v[244:247], v[164:165], off
	s_nop 0
	global_load_dwordx4 v[118:121], v[118:119], off offset:-512
	s_nop 0
	v_lshl_add_u64 v[166:167], v[122:123], 0, v[178:179]
	global_load_dwordx4 v[194:197], v[166:167], off
	s_nop 0
	global_load_dwordx4 v[122:125], v[122:123], off offset:-512
	ds_read_b64_tr_b16 v[218:219], v152 offset:0
	ds_read_b64_tr_b16 v[220:221], v152 offset:0x800
	ds_read_b64_tr_b16 v[222:223], v152 offset:0x1000
	ds_read_b64_tr_b16 v[224:225], v152 offset:0x1800
	ds_read_b64_tr_b16 v[226:227], v152 offset:0x2000
	ds_read_b64_tr_b16 v[228:229], v152 offset:0x2800
	ds_read_b64_tr_b16 v[230:231], v152 offset:0x3000
	ds_read_b64_tr_b16 v[232:233], v152 offset:0x3800
	s_waitcnt lgkmcnt(4)
; #define SBAR() __builtin_amdgcn_sched_barrier(0)
; __device__ __forceinline__ void partialSM(f32x16& p0, f32x16& p1, float& m_reg, float& mn, float& alpha, float C, float thrRaw) {
;   float pmax = p0[0];
; #pragma unroll
;   for (int r = 1; r < 16; ++r) pmax = fmaxf(pmax, p0[r]);
; #pragma unroll
;   for (int r = 0; r < 16; ++r) pmax = fmaxf(pmax, p1[r]);
;   { auto rr = __builtin_amdgcn_permlane32_swap(__float_as_uint(pmax), __float_as_uint(pmax), false, false);
;     pmax = fmaxf(__uint_as_float(rr[0]), __uint_as_float(rr[1])); }
;   if (__builtin_expect(__all(pmax - m_reg <= thrRaw), 1)) { mn = m_reg; alpha = 1.f; }
;   else { mn = fmaxf(m_reg, pmax); alpha = __builtin_amdgcn_exp2f((m_reg - mn) * C); m_reg = mn; }
; template <int D0> __device__ __forceinline__ void pv_one(f32x16& od, int vb, bf16x8 pa0, bf16x8 pa1, bf16x8 pa2, bf16x8 pa3) {
;   const s16x4 l0 = tr_read<v_rd_off(D0, 0, 0)>(vb), h0 = tr_read<v_rd_off(D0, 0, 1)>(vb), l1 = tr_read<v_rd_off(D0, 1, 0)>(vb), h1 = tr_read<v_rd_off(D0, 1, 1)>(vb);
;   const s16x4 l2 = tr_read<v_rd_off(D0, 2, 0)>(vb), h2 = tr_read<v_rd_off(D0, 2, 1)>(vb), l3 = tr_read<v_rd_off(D0, 3, 0)>(vb), h3 = tr_read<v_rd_off(D0, 3, 1)>(vb);
;   asm volatile("s_waitcnt lgkmcnt(0)" ::: "memory"); SBAR();
;     ...
;   od = __builtin_amdgcn_mfma_f32_32x32x16_bf16(pa0, PK(l0, h0), od, 0, 0, 0);
;   od = __builtin_amdgcn_mfma_f32_32x32x16_bf16(pa1, PK(l1, h1), od, 0, 0, 0);
;   od = __builtin_amdgcn_mfma_f32_32x32x16_bf16(pa2, PK(l2, h2), od, 0, 0, 0);
;   od = __builtin_amdgcn_mfma_f32_32x32x16_bf16(pa3, PK(l3, h3), od, 0, 0, 0);
;     ...
; }
; __device__ __forceinline__ void pv_d0(f32x16* o, int vb, bf16x8 pa0, bf16x8 pa1, bf16x8 pa2, bf16x8 pa3) {
;   pv_one<0>(o[0], vb, pa0, pa1, pa2, pa3); pv_one<1>(o[1], vb, pa0, pa1, pa2, pa3); pv_one<2>(o[2], vb, pa0, pa1, pa2, pa3); pv_one<3>(o[3], vb, pa0, pa1, pa2, pa3);
	s_nop 0
	v_mfma_f32_32x32x16_bf16 v[18:33], v[130:133], v[218:221], v[18:33]
	ds_read_b64_tr_b16 v[218:219], v152 offset:0x200
	ds_read_b64_tr_b16 v[220:221], v152 offset:0xa00
	v_mfma_f32_32x32x16_bf16 v[18:33], v[140:143], v[222:225], v[18:33]
	ds_read_b64_tr_b16 v[222:223], v152 offset:0x1200
	ds_read_b64_tr_b16 v[224:225], v152 offset:0x1a00
	s_waitcnt lgkmcnt(4)
	v_mfma_f32_32x32x16_bf16 v[18:33], v[136:139], v[226:229], v[18:33]
	ds_read_b64_tr_b16 v[226:227], v152 offset:0x2200
	ds_read_b64_tr_b16 v[228:229], v152 offset:0x2a00
	v_mfma_f32_32x32x16_bf16 v[18:33], v[214:217], v[230:233], v[18:33]
	ds_read_b64_tr_b16 v[230:231], v152 offset:0x3200
	ds_read_b64_tr_b16 v[232:233], v152 offset:0x3a00
	s_waitcnt lgkmcnt(4)
	v_mfma_f32_32x32x16_bf16 v[50:65], v[130:133], v[218:221], v[50:65]
	ds_read_b64_tr_b16 v[218:219], v152 offset:0x400
	ds_read_b64_tr_b16 v[220:221], v152 offset:0xc00
	v_mfma_f32_32x32x16_bf16 v[50:65], v[140:143], v[222:225], v[50:65]
	ds_read_b64_tr_b16 v[222:223], v152 offset:0x1400
	ds_read_b64_tr_b16 v[224:225], v152 offset:0x1c00
	s_waitcnt lgkmcnt(4)
	v_mfma_f32_32x32x16_bf16 v[50:65], v[136:139], v[226:229], v[50:65]
	ds_read_b64_tr_b16 v[226:227], v152 offset:0x2400
	ds_read_b64_tr_b16 v[228:229], v152 offset:0x2c00
	v_mfma_f32_32x32x16_bf16 v[50:65], v[214:217], v[230:233], v[50:65]
	ds_read_b64_tr_b16 v[230:231], v152 offset:0x3400
	ds_read_b64_tr_b16 v[232:233], v152 offset:0x3c00
	s_waitcnt lgkmcnt(4)
	v_mfma_f32_32x32x16_bf16 v[2:17], v[130:133], v[218:221], v[2:17]
	ds_read_b64_tr_b16 v[218:219], v152 offset:0x600
	ds_read_b64_tr_b16 v[220:221], v152 offset:0xe00
	v_mfma_f32_32x32x16_bf16 v[2:17], v[140:143], v[222:225], v[2:17]
	ds_read_b64_tr_b16 v[222:223], v152 offset:0x1600
	ds_read_b64_tr_b16 v[224:225], v152 offset:0x1e00
	s_waitcnt lgkmcnt(4)
	v_mfma_f32_32x32x16_bf16 v[2:17], v[136:139], v[226:229], v[2:17]
	ds_read_b64_tr_b16 v[226:227], v152 offset:0x2600
	ds_read_b64_tr_b16 v[228:229], v152 offset:0x2e00
	v_mfma_f32_32x32x16_bf16 v[2:17], v[214:217], v[230:233], v[2:17]
	ds_read_b64_tr_b16 v[230:231], v152 offset:0x3600
	ds_read_b64_tr_b16 v[232:233], v152 offset:0x3e00
	s_waitcnt lgkmcnt(6)
	v_mfma_f32_32x32x16_bf16 v[34:49], v[130:133], v[218:221], v[34:49]
	v_max_f32_e32 v130, v83, v82
	v_max3_f32 v130, v130, v84, v85
	v_max3_f32 v130, v130, v86, v87
	v_max3_f32 v130, v130, v88, v89
	v_max3_f32 v130, v130, v90, v91
	v_max3_f32 v130, v130, v92, v93
	v_max3_f32 v130, v130, v94, v95
	s_waitcnt lgkmcnt(4)
	v_mfma_f32_32x32x16_bf16 v[34:49], v[140:143], v[222:225], v[34:49]
	v_max3_f32 v130, v130, v96, v97
	v_max3_f32 v130, v130, v66, v67
	v_max3_f32 v130, v130, v68, v69
	v_max3_f32 v130, v130, v70, v71
	v_max3_f32 v130, v130, v72, v73
	v_max3_f32 v130, v130, v74, v75
	v_max3_f32 v130, v130, v76, v77
	v_max3_f32 v130, v130, v78, v79
	s_waitcnt lgkmcnt(2)
	v_mfma_f32_32x32x16_bf16 v[34:49], v[136:139], v[226:229], v[34:49]
	v_max3_f32 v130, v130, v80, v81
	v_mov_b32_e32 v131, v130
	s_nop 1
	v_permlane32_swap_b32_e32 v130, v131
	v_max_f32_e32 v130, v131, v130
	v_sub_f32_e32 v131, v130, v134
	s_mov_b32 s2, 0x42b504f3
	v_cmp_ge_f32_e32 vcc, s2, v131
	v_max_f32_e32 v130, v134, v130
	s_waitcnt lgkmcnt(0)
	v_mfma_f32_32x32x16_bf16 v[34:49], v[214:217], v[230:233], v[34:49]
	v_sub_f32_e32 v131, v134, v130
	v_mul_f32_e32 v131, 0x3e0293ee, v131
	v_exp_f32_e32 v131, v131
	s_cmp_eq_u64 vcc, exec
	s_cselect_b64 s[2:3], -1, 0
	s_waitcnt vmcnt(4)
	v_cndmask_b32_e64 v214, v131, 1.0, s[2:3]
	v_cmp_gt_f32_e32 vcc, 1.0, v214
	s_waitcnt vmcnt(4)
	ds_write_b128 v177, v[98:101] offset:32768
	ds_write_b128 v208, v[102:105] offset:32768
	s_cbranch_vccz .LBB0_664
	s_and_saveexec_b64 s[4:5], s[0:1]
	ds_write_b32 v149, v214 offset:128
	s_or_b64 exec, exec, s[4:5]
	s_waitcnt lgkmcnt(0)
	v_add_u32_e32 v131, v148, v0
	ds_read_b128 v[136:139], v131 offset:128
	ds_read_b128 v[140:143], v131 offset:160
	ds_read_b128 v[216:219], v131 offset:192
	ds_read_b128 v[220:223], v131 offset:224
	s_waitcnt lgkmcnt(3)
	v_pk_mul_f32 v[50:51], v[136:137], v[50:51]
	v_pk_mul_f32 v[52:53], v[52:53], v[138:139]
	s_waitcnt lgkmcnt(2)
	v_pk_mul_f32 v[54:55], v[54:55], v[140:141]
	v_pk_mul_f32 v[56:57], v[56:57], v[142:143]
	s_waitcnt lgkmcnt(1)
	v_pk_mul_f32 v[58:59], v[58:59], v[216:217]
	v_pk_mul_f32 v[60:61], v[60:61], v[218:219]
	s_waitcnt lgkmcnt(0)
	v_pk_mul_f32 v[62:63], v[62:63], v[220:221]
	v_pk_mul_f32 v[30:31], v[30:31], v[220:221]
	v_pk_mul_f32 v[26:27], v[26:27], v[216:217]
	v_pk_mul_f32 v[22:23], v[22:23], v[140:141]
	v_pk_mul_f32 v[32:33], v[32:33], v[222:223]
	v_pk_mul_f32 v[28:29], v[28:29], v[218:219]
	v_pk_mul_f32 v[24:25], v[24:25], v[142:143]
	v_pk_mul_f32 v[20:21], v[20:21], v[138:139]
	v_pk_mul_f32 v[18:19], v[18:19], v[136:137]
	v_pk_mul_f32 v[64:65], v[64:65], v[222:223]
	v_pk_mul_f32 v[34:35], v[136:137], v[34:35]
	v_pk_mul_f32 v[36:37], v[36:37], v[138:139]
	v_pk_mul_f32 v[38:39], v[38:39], v[140:141]
	v_pk_mul_f32 v[40:41], v[40:41], v[142:143]
	v_pk_mul_f32 v[42:43], v[42:43], v[216:217]
	v_pk_mul_f32 v[44:45], v[44:45], v[218:219]
	v_pk_mul_f32 v[46:47], v[46:47], v[220:221]
	v_pk_mul_f32 v[14:15], v[14:15], v[220:221]
	v_pk_mul_f32 v[10:11], v[10:11], v[216:217]
	v_pk_mul_f32 v[6:7], v[6:7], v[140:141]
	v_pk_mul_f32 v[16:17], v[16:17], v[222:223]
	v_pk_mul_f32 v[12:13], v[12:13], v[218:219]
	v_pk_mul_f32 v[8:9], v[8:9], v[142:143]
	v_pk_mul_f32 v[4:5], v[4:5], v[138:139]
	v_pk_mul_f32 v[2:3], v[2:3], v[136:137]
	v_pk_mul_f32 v[48:49], v[48:49], v[222:223]
; #define SBAR() __builtin_amdgcn_sched_barrier(0)
; #define SLOAD(i, k0) do { sr_[i].vs0 = *reinterpret_cast<const bf16x8*>(&Vh[(long)((k0) + sr) * LDP + sc]); sr_[i].vs1 = *reinterpret_cast<const bf16x8*>(&Vh[(long)((k0) + 32 + sr) * LDP + sc]); \
;     sr_[i].ks0 = *reinterpret_cast<const bf16x8*>(&Kh[(long)((k0) + ksr) * LDP + ksc]); if (DK == 128) sr_[i].ks1 = *reinterpret_cast<const bf16x8*>(&Kh[(long)((k0) + 32 + ksr) * LDP + ksc]); } while (0)
; #define SWAIT() do { if (SD == 1) asm volatile("s_waitcnt vmcnt(0)" ::: "memory"); else if (DK == 128) asm volatile("s_waitcnt vmcnt(4)" ::: "memory"); else asm volatile("s_waitcnt vmcnt(3)" ::: "memory"); } while (0)
; #define RESC(a) do { if (__any((a) < 1.f)) { if (hi == 0) al_l[r32] = (a); asm volatile("s_waitcnt lgkmcnt(0)" ::: "memory"); \
;     _Pragma("unroll") for (int d = 0; d < 4; ++d) _Pragma("unroll") for (int r = 0; r < 16; ++r) o[d][r] *= al_l[crow(r, hi)]; } } while (0)
; __device__ __forceinline__ void partialSM(f32x16& p0, f32x16& p1, float& m_reg, float& mn, float& alpha, float C, float thrRaw) {
;     ...
;   for (int r = 0; r < 16; ++r) p0[r] = fmaf(p0[r], C, mnC);
; #pragma unroll
;   for (int r = 0; r < 16; ++r) p1[r] = fmaf(p1[r], C, mnC);
; #pragma unroll
;   for (int r = 0; r < 16; ++r) p0[r] = __builtin_amdgcn_exp2f(p0[r]);
; }
; __device__ __forceinline__ void finishSM(f32x16& p0, f32x16& p1, float alpha, float& l_reg, bf16x8& pa0, bf16x8& pa1, bf16x8& pa2, bf16x8& pa3) {
; #pragma unroll
;   for (int r = 0; r < 16; ++r) p1[r] = __builtin_amdgcn_exp2f(p1[r]);
;   float ps = 0;
; #pragma unroll
;   for (int r = 0; r < 16; ++r) ps += p0[r];
; #pragma unroll
;   for (int r = 0; r < 16; ++r) ps += p1[r];
;   { auto rr = __builtin_amdgcn_permlane32_swap(__float_as_uint(ps), __float_as_uint(ps), false, false);
;     ps = __uint_as_float(rr[0]) + __uint_as_float(rr[1]); }
;   l_reg = l_reg * alpha + ps;
;     ...
;   PK4(p0, 0, pa0); PK4(p0, 8, pa1); PK4(p1, 0, pa2); PK4(p1, 8, pa3);
; template <int DK, bool NA, bool QL, int SD> ...
;     ...
;     __syncthreads(); SWAIT(); SWRITE(0, SE);
;     RESC(alB); __syncthreads();
;     SBAR(); qkt<DK, QL>(pA0, pA1, K_lds, qr, ql, r32, hi); HOOK(pA0, pA1, j + 1);
;     finishSM(pB0, pB1, alB, l_reg, pa0, pa1, pa2, pa3); SBAR();
;     if (SD == 1 || j + 3 < NT) SLOAD(SE, (j + 1 + SD) * KVBLK); SBAR();
.LBB0_664:
	v_cndmask_b32_e64 v215, v130, v134, s[2:3]
	v_mul_f32_e32 v216, 0xbe0293ee, v215
	s_mov_b32 s2, 0x3e0293ee
	v_pk_fma_f32 v[82:83], v[82:83], s[2:3], v[216:217] op_sel_hi:[1,0,0]
	v_pk_fma_f32 v[84:85], v[84:85], s[2:3], v[216:217] op_sel_hi:[1,0,0]
	v_pk_fma_f32 v[86:87], v[86:87], s[2:3], v[216:217] op_sel_hi:[1,0,0]
	v_pk_fma_f32 v[88:89], v[88:89], s[2:3], v[216:217] op_sel_hi:[1,0,0]
	v_pk_fma_f32 v[90:91], v[90:91], s[2:3], v[216:217] op_sel_hi:[1,0,0]
	v_pk_fma_f32 v[92:93], v[92:93], s[2:3], v[216:217] op_sel_hi:[1,0,0]
	v_pk_fma_f32 v[94:95], v[94:95], s[2:3], v[216:217] op_sel_hi:[1,0,0]
	v_pk_fma_f32 v[96:97], v[96:97], s[2:3], v[216:217] op_sel_hi:[1,0,0]
	v_exp_f32_e32 v130, v82
	v_exp_f32_e32 v145, v83
	v_exp_f32_e32 v131, v84
	v_exp_f32_e32 v144, v85
	v_exp_f32_e32 v132, v86
	v_exp_f32_e32 v143, v87
	v_exp_f32_e32 v133, v88
	v_exp_f32_e32 v142, v89
	v_exp_f32_e32 v134, v90
	v_exp_f32_e32 v141, v91
	v_exp_f32_e32 v135, v92
	v_exp_f32_e32 v140, v93
	v_exp_f32_e32 v136, v94
	v_exp_f32_e32 v139, v95
	v_exp_f32_e32 v137, v96
	v_exp_f32_e32 v138, v97
	v_fmamk_f32 v218, v71, 0x3e0293ee, v216
	v_fmamk_f32 v217, v78, 0x3e0293ee, v216
	s_add_i32 s8, s8, 2
	v_fmamk_f32 v225, v66, 0x3e0293ee, v216
	v_fmamk_f32 v226, v67, 0x3e0293ee, v216
	v_fmamk_f32 v227, v68, 0x3e0293ee, v216
	v_fmamk_f32 v228, v69, 0x3e0293ee, v216
	v_fmamk_f32 v229, v70, 0x3e0293ee, v216
	v_fmamk_f32 v219, v72, 0x3e0293ee, v216
	v_fmamk_f32 v220, v73, 0x3e0293ee, v216
	v_fmamk_f32 v221, v74, 0x3e0293ee, v216
	v_fmamk_f32 v222, v75, 0x3e0293ee, v216
	v_fmamk_f32 v223, v76, 0x3e0293ee, v216
	v_fmamk_f32 v224, v77, 0x3e0293ee, v216
	v_fmamk_f32 v230, v79, 0x3e0293ee, v216
	v_fmamk_f32 v231, v80, 0x3e0293ee, v216
	v_fmac_f32_e32 v216, 0x3e0293ee, v81
	s_waitcnt lgkmcnt(0)
	s_barrier
	ds_write_b128 v209, v[106:109]
	ds_write_b128 v210, v[110:113]
	ds_read_b128 v[66:69], v153
	ds_read_b128 v[70:73], v159 offset:32768
	ds_read_b128 v[74:77], v159 offset:40960
	ds_read_b128 v[232:235], v153 offset:1024
	ds_read_b128 v[236:239], v207 offset:32768
	ds_read_b128 v[240:243], v207 offset:40960
	v_exp_f32_e32 v174, v219
	v_exp_f32_e32 v219, v221
	s_waitcnt lgkmcnt(4)
	v_mfma_f32_32x32x16_bf16 v[82:97], v[70:73], v[66:69], 0
	v_exp_f32_e32 v221, v223
	v_exp_f32_e32 v223, v217
	v_add_f32_e32 v217, v145, v130
	v_add_f32_e32 v217, v131, v217
	v_add_f32_e32 v217, v144, v217
	v_add_f32_e32 v217, v132, v217
	s_waitcnt lgkmcnt(3)
	v_mfma_f32_32x32x16_bf16 v[66:81], v[74:77], v[66:69], 0
	v_add_f32_e32 v217, v143, v217
	v_add_f32_e32 v217, v133, v217
	v_add_f32_e32 v217, v142, v217
	v_add_f32_e32 v217, v134, v217
	v_add_f32_e32 v217, v141, v217
	v_add_f32_e32 v217, v135, v217
	v_add_f32_e32 v217, v140, v217
	s_waitcnt lgkmcnt(1)
	v_mfma_f32_32x32x16_bf16 v[82:97], v[236:239], v[232:235], v[82:97]
	v_exp_f32_e32 v164, v225
	v_add_f32_e32 v217, v136, v217
	v_exp_f32_e32 v165, v226
	v_add_f32_e32 v217, v139, v217
	v_exp_f32_e32 v166, v227
	v_add_f32_e32 v217, v137, v217
	v_exp_f32_e32 v167, v228
	s_waitcnt lgkmcnt(0)
	v_mfma_f32_32x32x16_bf16 v[66:81], v[240:243], v[232:235], v[66:81]
	ds_read_b128 v[232:235], v153 offset:2048
	ds_read_b128 v[236:239], v161 offset:32768
	ds_read_b128 v[240:243], v161 offset:40960
	v_add_f32_e32 v217, v138, v217
	v_exp_f32_e32 v172, v229
	v_add_f32_e32 v217, v164, v217
	v_exp_f32_e32 v173, v218
	v_add_f32_e32 v217, v165, v217
	v_add_f32_e32 v217, v166, v217
	s_waitcnt lgkmcnt(1)
	v_mfma_f32_32x32x16_bf16 v[82:97], v[236:239], v[232:235], v[82:97]
	v_exp_f32_e32 v175, v220
	v_add_f32_e32 v217, v167, v217
	v_add_f32_e32 v217, v172, v217
	v_exp_f32_e32 v220, v222
	v_add_f32_e32 v217, v173, v217
	v_add_f32_e32 v217, v174, v217
	v_exp_f32_e32 v222, v224
	s_waitcnt lgkmcnt(0)
	v_mfma_f32_32x32x16_bf16 v[66:81], v[240:243], v[232:235], v[66:81]
	ds_read_b128 v[232:235], v153 offset:3072
	ds_read_b128 v[236:239], v160 offset:32768
	ds_read_b128 v[240:243], v160 offset:40960
	v_add_f32_e32 v217, v175, v217
	v_add_f32_e32 v217, v219, v217
	v_exp_f32_e32 v224, v230
	v_add_f32_e32 v217, v220, v217
	v_exp_f32_e32 v225, v231
	v_add_f32_e32 v217, v221, v217
	s_waitcnt lgkmcnt(1)
	v_mfma_f32_32x32x16_bf16 v[82:97], v[236:239], v[232:235], v[82:97]
	v_exp_f32_e32 v216, v216
	v_add_f32_e32 v217, v222, v217
	v_add_f32_e32 v217, v223, v217
	v_add_f32_e32 v217, v224, v217
	v_add_f32_e32 v217, v225, v217
	v_add_f32_e32 v217, v216, v217
	v_mov_b32_e32 v218, v217
	s_waitcnt lgkmcnt(0)
	v_mfma_f32_32x32x16_bf16 v[66:81], v[240:243], v[232:235], v[66:81]
	ds_read_b128 v[232:235], v153 offset:4096
	ds_read_b128 v[236:239], v158 offset:32768
	ds_read_b128 v[240:243], v158 offset:40960
	v_permlane32_swap_b32_e32 v217, v218
	s_waitcnt lgkmcnt(1)
	v_mfma_f32_32x32x16_bf16 v[82:97], v[236:239], v[232:235], v[82:97]
	s_waitcnt lgkmcnt(0)
	v_mfma_f32_32x32x16_bf16 v[66:81], v[240:243], v[232:235], v[66:81]
	ds_read_b128 v[232:235], v153 offset:5120
	ds_read_b128 v[236:239], v156 offset:32768
	ds_read_b128 v[240:243], v156 offset:40960
	s_waitcnt lgkmcnt(1)
	v_mfma_f32_32x32x16_bf16 v[82:97], v[236:239], v[232:235], v[82:97]
	s_waitcnt lgkmcnt(0)
	v_mfma_f32_32x32x16_bf16 v[66:81], v[240:243], v[232:235], v[66:81]
	ds_read_b128 v[232:235], v153 offset:6144
	ds_read_b128 v[236:239], v157 offset:32768
	ds_read_b128 v[240:243], v157 offset:40960
	s_waitcnt lgkmcnt(1)
	v_mfma_f32_32x32x16_bf16 v[82:97], v[236:239], v[232:235], v[82:97]
	s_waitcnt lgkmcnt(0)
	v_mfma_f32_32x32x16_bf16 v[66:81], v[240:243], v[232:235], v[66:81]
	ds_read_b128 v[232:235], v153 offset:7168
	ds_read_b128 v[236:239], v176 offset:32768
	ds_read_b128 v[240:243], v176 offset:40960
	v_cvt_pk_bf16_f32 v130, v130, v145
	v_cvt_pk_bf16_f32 v131, v131, v144
	v_cvt_pk_bf16_f32 v132, v132, v143
	v_cvt_pk_bf16_f32 v133, v133, v142
	v_cvt_pk_bf16_f32 v134, v134, v141
	v_cvt_pk_bf16_f32 v135, v135, v140
	s_waitcnt lgkmcnt(1)
	v_mfma_f32_32x32x16_bf16 v[82:97], v[236:239], v[232:235], v[82:97]
	v_cvt_pk_bf16_f32 v136, v136, v139
	v_cvt_pk_bf16_f32 v137, v137, v138
	v_cvt_pk_bf16_f32 v138, v164, v165
	v_cvt_pk_bf16_f32 v139, v166, v167
	v_cvt_pk_bf16_f32 v140, v172, v173
	v_cvt_pk_bf16_f32 v141, v174, v175
	v_cvt_pk_bf16_f32 v142, v219, v220
	s_waitcnt lgkmcnt(0)
	v_mfma_f32_32x32x16_bf16 v[66:81], v[240:243], v[232:235], v[66:81]
	v_cvt_pk_bf16_f32 v143, v221, v222
	v_cvt_pk_bf16_f32 v144, v223, v224
	v_cvt_pk_bf16_f32 v145, v225, v216
	s_cmp_gt_u32 s8, 60
	s_cselect_b64 s[4:5], -1, 0
	s_and_b64 vcc, exec, s[4:5]
	s_cbranch_vccnz .Lod_gqa
	v_add_co_u32_e32 v98, vcc, 0xfffb0000, v146
	s_nop 1
	v_addc_co_u32_e32 v99, vcc, -1, v147, vcc
	v_lshl_add_u64 v[164:165], v[98:99], 0, v[178:179]
	global_load_dwordx4 v[106:109], v[164:165], off
	s_nop 0
	global_load_dwordx4 v[98:101], v[98:99], off offset:-512
	s_nop 0
	v_lshl_add_u64 v[166:167], v[146:147], 0, v[178:179]
	global_load_dwordx4 v[110:113], v[166:167], off
	global_load_dwordx4 v[102:105], v[146:147], off offset:-512

; #define SBAR() __builtin_amdgcn_sched_barrier(0)
; #define HOOK(P0, P1, j) do { if (NA) na_hook(P0, P1, krow0 + (j), q_row, q_col, win_r, win_c, rpb, inv_scale, hi); } while (0)
; __device__ __forceinline__ void finishSM(f32x16& p0, f32x16& p1, float alpha, float& l_reg, bf16x8& pa0, bf16x8& pa1, bf16x8& pa2, bf16x8& pa3) {
; #pragma unroll
;   for (int r = 0; r < 16; ++r) p1[r] = __builtin_amdgcn_exp2f(p1[r]);
;   float ps = 0;
; #pragma unroll
;   for (int r = 0; r < 16; ++r) ps += p0[r];
; #pragma unroll
;   for (int r = 0; r < 16; ++r) ps += p1[r];
;   { auto rr = __builtin_amdgcn_permlane32_swap(__float_as_uint(ps), __float_as_uint(ps), false, false);
;     ps = __uint_as_float(rr[0]) + __uint_as_float(rr[1]); }
;   l_reg = l_reg * alpha + ps;
;     ...
;   PK4(p0, 0, pa0); PK4(p0, 8, pa1); PK4(p1, 0, pa2); PK4(p1, 8, pa3);
; template <int DK, bool NA, bool QL, int SD> ...
;     ...
;   SBAR(); qkt<DK, QL>(pB0, pB1, (bf16*)((char*)K_lds + SHM_K), qr, ql, r32, hi); HOOK(pB0, pB1, NT - 1);
;   finishSM(pA0, pA1, alA, l_reg, pa0, pa1, pa2, pa3); SBAR();
;   pv_d0(o, vb0, pa0, pa1, pa2, pa3); partialSM(pB0, pB1, m_reg, mnB, alB, C, thrRaw);
.LBB0_672:
	ds_write_b128 v209, v[244:247] offset:16384
	ds_write_b128 v210, v[194:197] offset:16384
	ds_read_b128 v[66:69], v153
	ds_read_b128 v[70:73], v159 offset:49152
	ds_read_b128 v[74:77], v159 offset:57344
	ds_read_b128 v[98:101], v153 offset:1024
	ds_read_b128 v[102:105], v207 offset:49152
	ds_read_b128 v[106:109], v207 offset:57344
	v_exp_f32_e32 v110, v124
	v_exp_f32_e32 v111, v125
	s_waitcnt lgkmcnt(4)
	v_mfma_f32_32x32x16_bf16 v[82:97], v[70:73], v[66:69], 0
	v_exp_f32_e32 v112, v118
	v_exp_f32_e32 v113, v119
	v_exp_f32_e32 v116, v116
	v_exp_f32_e32 v117, v117
	v_exp_f32_e32 v114, v114
	v_exp_f32_e32 v115, v115
	v_exp_f32_e32 v118, v128
	s_waitcnt lgkmcnt(3)
	v_mfma_f32_32x32x16_bf16 v[66:81], v[74:77], v[66:69], 0
	v_exp_f32_e32 v119, v129
	v_exp_f32_e32 v122, v122
	v_exp_f32_e32 v123, v123
	v_exp_f32_e32 v120, v120
	v_exp_f32_e32 v121, v121
	s_waitcnt lgkmcnt(1)
	v_mfma_f32_32x32x16_bf16 v[82:97], v[102:105], v[98:101], v[82:97]
	s_waitcnt lgkmcnt(0)
	v_mfma_f32_32x32x16_bf16 v[66:81], v[106:109], v[98:101], v[66:81]
	ds_read_b128 v[98:101], v153 offset:2048
	ds_read_b128 v[102:105], v161 offset:49152
	ds_read_b128 v[106:109], v161 offset:57344
	s_waitcnt lgkmcnt(1)
	v_mfma_f32_32x32x16_bf16 v[82:97], v[102:105], v[98:101], v[82:97]
	s_waitcnt lgkmcnt(0)
	v_mfma_f32_32x32x16_bf16 v[66:81], v[106:109], v[98:101], v[66:81]
	ds_read_b128 v[98:101], v153 offset:3072
	ds_read_b128 v[102:105], v160 offset:49152
	ds_read_b128 v[106:109], v160 offset:57344
	s_waitcnt lgkmcnt(1)
	v_mfma_f32_32x32x16_bf16 v[82:97], v[102:105], v[98:101], v[82:97]
	s_waitcnt lgkmcnt(0)
	v_mfma_f32_32x32x16_bf16 v[66:81], v[106:109], v[98:101], v[66:81]
	ds_read_b128 v[98:101], v153 offset:4096
	ds_read_b128 v[102:105], v158 offset:49152
	ds_read_b128 v[106:109], v158 offset:57344
	s_waitcnt lgkmcnt(1)
	v_mfma_f32_32x32x16_bf16 v[82:97], v[102:105], v[98:101], v[82:97]
	s_waitcnt lgkmcnt(0)
	v_mfma_f32_32x32x16_bf16 v[66:81], v[106:109], v[98:101], v[66:81]
	ds_read_b128 v[98:101], v153 offset:5120
	ds_read_b128 v[102:105], v156 offset:49152
	ds_read_b128 v[106:109], v156 offset:57344
	s_waitcnt lgkmcnt(1)
	v_mfma_f32_32x32x16_bf16 v[82:97], v[102:105], v[98:101], v[82:97]
	s_waitcnt lgkmcnt(0)
	v_mfma_f32_32x32x16_bf16 v[66:81], v[106:109], v[98:101], v[66:81]
	ds_read_b128 v[98:101], v153 offset:6144
	ds_read_b128 v[102:105], v157 offset:49152
	ds_read_b128 v[106:109], v157 offset:57344
	s_waitcnt lgkmcnt(1)
	v_mfma_f32_32x32x16_bf16 v[82:97], v[102:105], v[98:101], v[82:97]
	s_waitcnt lgkmcnt(0)
	v_mfma_f32_32x32x16_bf16 v[66:81], v[106:109], v[98:101], v[66:81]
	ds_read_b128 v[98:101], v153 offset:7168
	ds_read_b128 v[102:105], v176 offset:49152
	ds_read_b128 v[106:109], v176 offset:57344
	s_waitcnt lgkmcnt(1)
	v_mfma_f32_32x32x16_bf16 v[82:97], v[102:105], v[98:101], v[82:97]
	s_waitcnt lgkmcnt(0)
	v_mfma_f32_32x32x16_bf16 v[66:81], v[106:109], v[98:101], v[66:81]
	v_add_f32_e32 v98, 0, v145
	v_add_f32_e32 v98, v216, v98
	v_add_f32_e32 v98, v131, v98
	v_add_f32_e32 v98, v215, v98
	v_add_f32_e32 v98, v132, v98
	v_add_f32_e32 v98, v144, v98
	v_add_f32_e32 v98, v133, v98
	v_add_f32_e32 v98, v143, v98
	v_add_f32_e32 v98, v140, v98
	v_add_f32_e32 v98, v142, v98
	v_add_f32_e32 v98, v139, v98
	v_add_f32_e32 v98, v141, v98
	v_exp_f32_e32 v108, v126
	v_add_f32_e32 v98, v136, v98
	v_exp_f32_e32 v109, v127
	v_add_f32_e32 v98, v138, v98
	v_add_f32_e32 v98, v135, v98
	v_add_f32_e32 v98, v137, v98
	v_add_f32_e32 v98, v108, v98
	v_add_f32_e32 v98, v109, v98
	v_add_f32_e32 v98, v110, v98
	v_add_f32_e32 v98, v111, v98
	v_add_f32_e32 v98, v112, v98
	v_add_f32_e32 v98, v113, v98
	v_add_f32_e32 v98, v116, v98
	v_add_f32_e32 v98, v117, v98
	v_add_f32_e32 v98, v114, v98
	v_add_f32_e32 v98, v115, v98
	v_add_f32_e32 v98, v118, v98
	v_add_f32_e32 v98, v119, v98
	v_add_f32_e32 v98, v122, v98
	v_add_f32_e32 v98, v123, v98
	v_add_f32_e32 v98, v120, v98
	v_add_f32_e32 v102, v121, v98
	v_mov_b32_e32 v103, v102
	v_cvt_pk_bf16_f32 v98, v145, v216
	v_cvt_pk_bf16_f32 v99, v131, v215
	v_cvt_pk_bf16_f32 v100, v132, v144
	v_cvt_pk_bf16_f32 v101, v133, v143
	s_nop 1
	v_permlane32_swap_b32_e32 v102, v103
	v_cvt_pk_bf16_f32 v104, v140, v142
	v_cvt_pk_bf16_f32 v105, v139, v141
	v_cvt_pk_bf16_f32 v106, v136, v138
	v_cvt_pk_bf16_f32 v107, v135, v137
	v_cvt_pk_bf16_f32 v108, v108, v109
	v_cvt_pk_bf16_f32 v109, v110, v111
	v_cvt_pk_bf16_f32 v110, v112, v113
	v_cvt_pk_bf16_f32 v111, v116, v117
	v_cvt_pk_bf16_f32 v112, v114, v115
	v_cvt_pk_bf16_f32 v113, v118, v119
	v_cvt_pk_bf16_f32 v114, v122, v123
	v_cvt_pk_bf16_f32 v115, v120, v121
	s_nop 0
	ds_read_b64_tr_b16 v[116:117], v152 offset:0
	ds_read_b64_tr_b16 v[118:119], v152 offset:0x800
	ds_read_b64_tr_b16 v[120:121], v152 offset:0x1000
	ds_read_b64_tr_b16 v[122:123], v152 offset:0x1800
	ds_read_b64_tr_b16 v[124:125], v152 offset:0x2000
	ds_read_b64_tr_b16 v[126:127], v152 offset:0x2800
	ds_read_b64_tr_b16 v[136:137], v152 offset:0x3000
	ds_read_b64_tr_b16 v[138:139], v152 offset:0x3800
	s_waitcnt lgkmcnt(0)
	s_nop 0
	v_mfma_f32_32x32x16_bf16 v[18:33], v[98:101], v[116:119], v[18:33]
	ds_read_b64_tr_b16 v[116:117], v152 offset:0x200
	ds_read_b64_tr_b16 v[118:119], v152 offset:0xa00
	v_mfma_f32_32x32x16_bf16 v[18:33], v[104:107], v[120:123], v[18:33]
	ds_read_b64_tr_b16 v[120:121], v152 offset:0x1200
	ds_read_b64_tr_b16 v[122:123], v152 offset:0x1a00
	v_mfma_f32_32x32x16_bf16 v[18:33], v[108:111], v[124:127], v[18:33]
	ds_read_b64_tr_b16 v[124:125], v152 offset:0x2200
	ds_read_b64_tr_b16 v[126:127], v152 offset:0x2a00
	v_mfma_f32_32x32x16_bf16 v[18:33], v[112:115], v[136:139], v[18:33]
	ds_read_b64_tr_b16 v[136:137], v152 offset:0x3200
	ds_read_b64_tr_b16 v[138:139], v152 offset:0x3a00
	s_waitcnt lgkmcnt(0)
; #define RESC(a) do { if (__any((a) < 1.f)) { if (hi == 0) al_l[r32] = (a); asm volatile("s_waitcnt lgkmcnt(0)" ::: "memory"); \
;     _Pragma("unroll") for (int d = 0; d < 4; ++d) _Pragma("unroll") for (int r = 0; r < 16; ++r) o[d][r] *= al_l[crow(r, hi)]; } } while (0)
; __device__ __forceinline__ void partialSM(f32x16& p0, f32x16& p1, float& m_reg, float& mn, float& alpha, float C, float thrRaw) {
;   float pmax = p0[0];
; #pragma unroll
;   for (int r = 1; r < 16; ++r) pmax = fmaxf(pmax, p0[r]);
; #pragma unroll
;   for (int r = 0; r < 16; ++r) pmax = fmaxf(pmax, p1[r]);
;   { auto rr = __builtin_amdgcn_permlane32_swap(__float_as_uint(pmax), __float_as_uint(pmax), false, false);
;     pmax = fmaxf(__uint_as_float(rr[0]), __uint_as_float(rr[1])); }
;   if (__builtin_expect(__all(pmax - m_reg <= thrRaw), 1)) { mn = m_reg; alpha = 1.f; }
;   else { mn = fmaxf(m_reg, pmax); alpha = __builtin_amdgcn_exp2f((m_reg - mn) * C); m_reg = mn; }
; template <int DK, bool NA, bool QL, int SD> ...
;     ...
;   pv_d0(o, vb0, pa0, pa1, pa2, pa3); partialSM(pB0, pB1, m_reg, mnB, alB, C, thrRaw);
;   __syncthreads(); RESC(alB);
	v_mfma_f32_32x32x16_bf16 v[50:65], v[98:101], v[116:119], v[50:65]
	ds_read_b64_tr_b16 v[116:117], v152 offset:0x400
	ds_read_b64_tr_b16 v[118:119], v152 offset:0xc00
	v_mfma_f32_32x32x16_bf16 v[50:65], v[104:107], v[120:123], v[50:65]
	ds_read_b64_tr_b16 v[120:121], v152 offset:0x1400
	ds_read_b64_tr_b16 v[122:123], v152 offset:0x1c00
	v_mfma_f32_32x32x16_bf16 v[50:65], v[108:111], v[124:127], v[50:65]
	ds_read_b64_tr_b16 v[124:125], v152 offset:0x2400
	ds_read_b64_tr_b16 v[126:127], v152 offset:0x2c00
	v_mfma_f32_32x32x16_bf16 v[50:65], v[112:115], v[136:139], v[50:65]
	ds_read_b64_tr_b16 v[136:137], v152 offset:0x3400
	ds_read_b64_tr_b16 v[138:139], v152 offset:0x3c00
	s_waitcnt lgkmcnt(0)
	v_mfma_f32_32x32x16_bf16 v[2:17], v[98:101], v[116:119], v[2:17]
	ds_read_b64_tr_b16 v[116:117], v152 offset:0x600
	ds_read_b64_tr_b16 v[118:119], v152 offset:0xe00
	v_mfma_f32_32x32x16_bf16 v[2:17], v[104:107], v[120:123], v[2:17]
	ds_read_b64_tr_b16 v[120:121], v152 offset:0x1600
	ds_read_b64_tr_b16 v[122:123], v152 offset:0x1e00
	v_mfma_f32_32x32x16_bf16 v[2:17], v[108:111], v[124:127], v[2:17]
	ds_read_b64_tr_b16 v[124:125], v152 offset:0x2600
	ds_read_b64_tr_b16 v[126:127], v152 offset:0x2e00
	v_mfma_f32_32x32x16_bf16 v[2:17], v[112:115], v[136:139], v[2:17]
	ds_read_b64_tr_b16 v[136:137], v152 offset:0x3600
	ds_read_b64_tr_b16 v[138:139], v152 offset:0x3e00
	s_waitcnt lgkmcnt(0)
	v_mfma_f32_32x32x16_bf16 v[34:49], v[98:101], v[116:119], v[34:49]
	v_max_f32_e32 v98, v83, v83
	v_max_f32_e32 v99, v82, v82
	v_max_f32_e32 v98, v99, v98
	v_max3_f32 v98, v98, v84, v85
	v_max3_f32 v98, v98, v86, v87
	v_max3_f32 v98, v98, v88, v89
	v_max3_f32 v98, v98, v90, v91
	v_max3_f32 v98, v98, v92, v93
	v_max3_f32 v98, v98, v94, v95
	v_mfma_f32_32x32x16_bf16 v[34:49], v[104:107], v[120:123], v[34:49]
	v_max3_f32 v98, v98, v96, v97
	v_max3_f32 v98, v98, v66, v67
	v_max3_f32 v98, v98, v68, v69
	v_max3_f32 v98, v98, v70, v71
	v_max3_f32 v98, v98, v72, v73
	v_max3_f32 v98, v98, v74, v75
	v_max3_f32 v98, v98, v76, v77
	v_max3_f32 v98, v98, v78, v79
	v_mfma_f32_32x32x16_bf16 v[34:49], v[108:111], v[124:127], v[34:49]
	v_max3_f32 v98, v98, v80, v81
	v_mov_b32_e32 v99, v98
	s_nop 1
	v_permlane32_swap_b32_e32 v98, v99
	v_max_f32_e32 v99, v99, v99
	v_max_f32_e32 v98, v98, v98
	v_max_f32_e32 v98, v98, v99
	v_sub_f32_e32 v99, v98, v134
	s_mov_b32 s2, 0x42b504f3
	v_cmp_ge_f32_e32 vcc, s2, v99
	v_max_f32_e32 v99, v134, v134
	v_max_f32_e32 v99, v99, v98
	v_mfma_f32_32x32x16_bf16 v[34:49], v[112:115], v[136:139], v[34:49]
	v_sub_f32_e32 v98, v134, v99
	v_mul_f32_e32 v98, 0x3e0293ee, v98
	v_exp_f32_e32 v98, v98
	s_cmp_eq_u64 vcc, exec
	s_cselect_b64 s[2:3], -1, 0
	v_cndmask_b32_e64 v98, v98, 1.0, s[2:3]
	v_cmp_gt_f32_e32 vcc, 1.0, v98
	s_barrier
	s_cbranch_vccz .LBB0_676
	s_and_saveexec_b64 s[4:5], s[0:1]
	ds_write_b32 v149, v98 offset:128
	s_or_b64 exec, exec, s[4:5]
	s_waitcnt lgkmcnt(0)
	v_add_u32_e32 v100, v148, v0
	ds_read_b128 v[104:107], v100 offset:128
	ds_read_b128 v[108:111], v100 offset:160
	ds_read_b128 v[112:115], v100 offset:192
	ds_read_b128 v[116:119], v100 offset:224
	s_waitcnt lgkmcnt(3)
	v_pk_mul_f32 v[50:51], v[104:105], v[50:51]
	v_pk_mul_f32 v[52:53], v[52:53], v[106:107]
	s_waitcnt lgkmcnt(2)
	v_pk_mul_f32 v[54:55], v[54:55], v[108:109]
	v_pk_mul_f32 v[56:57], v[56:57], v[110:111]
	s_waitcnt lgkmcnt(1)
	v_pk_mul_f32 v[58:59], v[58:59], v[112:113]
	v_pk_mul_f32 v[60:61], v[60:61], v[114:115]
	s_waitcnt lgkmcnt(0)
	v_pk_mul_f32 v[62:63], v[62:63], v[116:117]
	v_pk_mul_f32 v[30:31], v[30:31], v[116:117]
	v_pk_mul_f32 v[26:27], v[26:27], v[112:113]
	v_pk_mul_f32 v[22:23], v[22:23], v[108:109]
	v_pk_mul_f32 v[32:33], v[32:33], v[118:119]
	v_pk_mul_f32 v[28:29], v[28:29], v[114:115]
	v_pk_mul_f32 v[24:25], v[24:25], v[110:111]
	v_pk_mul_f32 v[20:21], v[20:21], v[106:107]
	v_pk_mul_f32 v[18:19], v[18:19], v[104:105]
	v_pk_mul_f32 v[64:65], v[64:65], v[118:119]
	v_pk_mul_f32 v[34:35], v[104:105], v[34:35]
	v_pk_mul_f32 v[36:37], v[36:37], v[106:107]
	v_pk_mul_f32 v[38:39], v[38:39], v[108:109]
	v_pk_mul_f32 v[40:41], v[40:41], v[110:111]
	v_pk_mul_f32 v[42:43], v[42:43], v[112:113]
	v_pk_mul_f32 v[44:45], v[44:45], v[114:115]
	v_pk_mul_f32 v[46:47], v[46:47], v[116:117]
	v_pk_mul_f32 v[14:15], v[14:15], v[116:117]
	v_pk_mul_f32 v[10:11], v[10:11], v[112:113]
	v_pk_mul_f32 v[6:7], v[6:7], v[108:109]
	v_pk_mul_f32 v[16:17], v[16:17], v[118:119]
	v_pk_mul_f32 v[12:13], v[12:13], v[114:115]
	v_pk_mul_f32 v[8:9], v[8:9], v[110:111]
	v_pk_mul_f32 v[4:5], v[4:5], v[106:107]
	v_pk_mul_f32 v[2:3], v[2:3], v[104:105]
	v_pk_mul_f32 v[48:49], v[48:49], v[118:119]
; #define SBAR() __builtin_amdgcn_sched_barrier(0)
; __device__ __forceinline__ void finishSM(f32x16& p0, f32x16& p1, float alpha, float& l_reg, bf16x8& pa0, bf16x8& pa1, bf16x8& pa2, bf16x8& pa3) {
; #pragma unroll
;   for (int r = 0; r < 16; ++r) p1[r] = __builtin_amdgcn_exp2f(p1[r]);
;   float ps = 0;
; #pragma unroll
;   for (int r = 0; r < 16; ++r) ps += p0[r];
; #pragma unroll
;   for (int r = 0; r < 16; ++r) ps += p1[r];
;   { auto rr = __builtin_amdgcn_permlane32_swap(__float_as_uint(ps), __float_as_uint(ps), false, false);
;     ps = __uint_as_float(rr[0]) + __uint_as_float(rr[1]); }
;   l_reg = l_reg * alpha + ps;
;     ...
;   PK4(p0, 0, pa0); PK4(p0, 8, pa1); PK4(p1, 0, pa2); PK4(p1, 8, pa3);
; template <int DK, bool NA, bool QL, int SD> ...
;     ...
;   finishSM(pB0, pB1, alB, l_reg, pa0, pa1, pa2, pa3); SBAR();
;   pv_d0(o, vb0 + (int)SHM_V, pa0, pa1, pa2, pa3);
.LBB0_676:
	v_cndmask_b32_e64 v99, v99, v134, s[2:3]
	v_mul_f32_e32 v99, 0xbe0293ee, v99
	v_fmamk_f32 v82, v82, 0x3e0293ee, v99
	v_fmamk_f32 v83, v83, 0x3e0293ee, v99
	v_fmamk_f32 v100, v84, 0x3e0293ee, v99
	v_exp_f32_e32 v84, v82
	v_fmamk_f32 v101, v86, 0x3e0293ee, v99
	v_exp_f32_e32 v86, v83
	v_fmamk_f32 v85, v85, 0x3e0293ee, v99
	v_exp_f32_e32 v82, v100
	v_fmamk_f32 v66, v66, 0x3e0293ee, v99
	v_exp_f32_e32 v85, v85
	v_fmamk_f32 v104, v87, 0x3e0293ee, v99
	v_fmamk_f32 v113, v96, 0x3e0293ee, v99
	v_fmamk_f32 v96, v77, 0x3e0293ee, v99
	v_exp_f32_e32 v77, v101
	v_exp_f32_e32 v100, v66
	v_add_f32_e32 v66, 0, v84
	v_fmamk_f32 v105, v88, 0x3e0293ee, v99
	v_exp_f32_e32 v83, v104
	v_add_f32_e32 v66, v86, v66
	v_fmamk_f32 v106, v89, 0x3e0293ee, v99
	v_fmamk_f32 v112, v95, 0x3e0293ee, v99
	v_fmamk_f32 v95, v76, 0x3e0293ee, v99
	v_exp_f32_e32 v76, v105
	v_add_f32_e32 v66, v82, v66
	v_fmamk_f32 v107, v90, 0x3e0293ee, v99
	v_fmamk_f32 v114, v97, 0x3e0293ee, v99
	v_fmamk_f32 v97, v78, 0x3e0293ee, v99
	v_exp_f32_e32 v78, v106
	v_add_f32_e32 v66, v85, v66
	v_fmamk_f32 v108, v91, 0x3e0293ee, v99
	v_fmamk_f32 v109, v92, 0x3e0293ee, v99
	v_fmamk_f32 v92, v73, 0x3e0293ee, v99
	v_exp_f32_e32 v73, v107
	v_add_f32_e32 v66, v77, v66
	v_fmamk_f32 v111, v94, 0x3e0293ee, v99
	v_fmamk_f32 v94, v75, 0x3e0293ee, v99
	v_exp_f32_e32 v75, v108
	v_add_f32_e32 v66, v83, v66
	v_fmamk_f32 v110, v93, 0x3e0293ee, v99
	v_fmamk_f32 v90, v71, 0x3e0293ee, v99
	v_exp_f32_e32 v71, v109
	v_add_f32_e32 v66, v76, v66
	v_fmamk_f32 v93, v74, 0x3e0293ee, v99
	v_exp_f32_e32 v74, v110
	v_add_f32_e32 v66, v78, v66
	v_fmamk_f32 v88, v69, 0x3e0293ee, v99
	v_exp_f32_e32 v69, v111
	v_add_f32_e32 v66, v73, v66
	v_fmamk_f32 v91, v72, 0x3e0293ee, v99
	v_exp_f32_e32 v72, v112
	v_add_f32_e32 v66, v75, v66
	v_fmamk_f32 v87, v68, 0x3e0293ee, v99
	v_exp_f32_e32 v68, v113
	v_add_f32_e32 v66, v71, v66
	v_fmamk_f32 v89, v70, 0x3e0293ee, v99
	v_exp_f32_e32 v70, v114
	v_add_f32_e32 v66, v74, v66
	v_fmamk_f32 v67, v67, 0x3e0293ee, v99
	v_add_f32_e32 v66, v69, v66
	v_exp_f32_e32 v101, v67
	v_add_f32_e32 v66, v72, v66
	v_exp_f32_e32 v87, v87
	v_add_f32_e32 v66, v68, v66
	v_exp_f32_e32 v88, v88
	v_add_f32_e32 v66, v70, v66
	v_exp_f32_e32 v89, v89
	v_add_f32_e32 v66, v100, v66
	v_exp_f32_e32 v90, v90
	v_add_f32_e32 v66, v101, v66
	v_exp_f32_e32 v91, v91
	v_add_f32_e32 v66, v87, v66
	v_exp_f32_e32 v92, v92
	v_add_f32_e32 v66, v88, v66
	v_exp_f32_e32 v93, v93
	v_add_f32_e32 v66, v89, v66
	v_exp_f32_e32 v94, v94
	v_add_f32_e32 v66, v90, v66
	v_exp_f32_e32 v95, v95
	v_add_f32_e32 v66, v91, v66
	v_exp_f32_e32 v96, v96
	v_add_f32_e32 v66, v92, v66
	v_fmamk_f32 v79, v79, 0x3e0293ee, v99
	v_exp_f32_e32 v97, v97
	v_add_f32_e32 v66, v93, v66
	v_fmamk_f32 v80, v80, 0x3e0293ee, v99
	v_exp_f32_e32 v104, v79
	v_add_f32_e32 v66, v94, v66
	v_fmac_f32_e32 v99, 0x3e0293ee, v81
	v_exp_f32_e32 v105, v80
	v_add_f32_e32 v66, v95, v66
	v_exp_f32_e32 v99, v99
	v_add_f32_e32 v66, v96, v66
	v_add_f32_e32 v66, v97, v66
	v_add_f32_e32 v66, v104, v66
	v_add_f32_e32 v66, v105, v66
	v_add_f32_e32 v66, v99, v66
	v_mov_b32_e32 v67, v66
	s_mov_b64 s[4:5], 0x800
	s_nop 0
	v_permlane32_swap_b32_e32 v66, v67
	v_cvt_pk_bf16_f32 v80, v84, v86
	v_cvt_pk_bf16_f32 v81, v82, v85
	v_cvt_pk_bf16_f32 v82, v77, v83
	v_cvt_pk_bf16_f32 v83, v76, v78
	v_cvt_pk_bf16_f32 v76, v73, v75
	v_cvt_pk_bf16_f32 v77, v71, v74
	v_cvt_pk_bf16_f32 v78, v69, v72
	v_cvt_pk_bf16_f32 v79, v68, v70
	v_cvt_pk_bf16_f32 v68, v100, v101
	v_cvt_pk_bf16_f32 v69, v87, v88
	v_cvt_pk_bf16_f32 v70, v89, v90
	v_cvt_pk_bf16_f32 v71, v91, v92
	v_cvt_pk_bf16_f32 v72, v93, v94
	v_cvt_pk_bf16_f32 v73, v95, v96
	v_cvt_pk_bf16_f32 v74, v97, v104
	v_cvt_pk_bf16_f32 v75, v105, v99
	s_nop 0
	ds_read_b64_tr_b16 v[84:85], v151 offset:0
	ds_read_b64_tr_b16 v[86:87], v151 offset:0x800
	ds_read_b64_tr_b16 v[88:89], v151 offset:0x1000
	ds_read_b64_tr_b16 v[90:91], v151 offset:0x1800
	ds_read_b64_tr_b16 v[92:93], v151 offset:0x2000
	ds_read_b64_tr_b16 v[94:95], v151 offset:0x2800
	ds_read_b64_tr_b16 v[104:105], v151 offset:0x3000
	ds_read_b64_tr_b16 v[106:107], v151 offset:0x3800
	s_waitcnt lgkmcnt(0)
	s_nop 0
	v_mfma_f32_32x32x16_bf16 v[18:33], v[80:83], v[84:87], v[18:33]
	ds_read_b64_tr_b16 v[84:85], v151 offset:0x200
	ds_read_b64_tr_b16 v[86:87], v151 offset:0xa00
	v_mfma_f32_32x32x16_bf16 v[18:33], v[76:79], v[88:91], v[18:33]
	ds_read_b64_tr_b16 v[88:89], v151 offset:0x1200
	ds_read_b64_tr_b16 v[90:91], v151 offset:0x1a00
	v_mfma_f32_32x32x16_bf16 v[18:33], v[68:71], v[92:95], v[18:33]
	ds_read_b64_tr_b16 v[92:93], v151 offset:0x2200
	ds_read_b64_tr_b16 v[94:95], v151 offset:0x2a00
	v_mfma_f32_32x32x16_bf16 v[18:33], v[72:75], v[104:107], v[18:33]
	ds_read_b64_tr_b16 v[104:105], v151 offset:0x3200
	ds_read_b64_tr_b16 v[106:107], v151 offset:0x3a00
	s_waitcnt lgkmcnt(0)
	v_mfma_f32_32x32x16_bf16 v[50:65], v[80:83], v[84:87], v[50:65]
	ds_read_b64_tr_b16 v[84:85], v151 offset:0x400
	ds_read_b64_tr_b16 v[86:87], v151 offset:0xc00
	v_mfma_f32_32x32x16_bf16 v[50:65], v[76:79], v[88:91], v[50:65]
	ds_read_b64_tr_b16 v[88:89], v151 offset:0x1400
	ds_read_b64_tr_b16 v[90:91], v151 offset:0x1c00
	v_mfma_f32_32x32x16_bf16 v[50:65], v[68:71], v[92:95], v[50:65]
	ds_read_b64_tr_b16 v[92:93], v151 offset:0x2400
	ds_read_b64_tr_b16 v[94:95], v151 offset:0x2c00
	v_mfma_f32_32x32x16_bf16 v[50:65], v[72:75], v[104:107], v[50:65]
	ds_read_b64_tr_b16 v[104:105], v151 offset:0x3400
	ds_read_b64_tr_b16 v[106:107], v151 offset:0x3c00
	s_waitcnt lgkmcnt(0)
; __device__ __forceinline__ int opaque_tid() { int t = threadIdx.x; asm volatile("" : "+v"(t)); return t; }
; #define SBAR() __builtin_amdgcn_sched_barrier(0)
; __device__ __forceinline__ int crow(int r, int hi) { return (r & 3) + 8 * (r >> 2) + 4 * hi; }
; template <int DK, bool NA, bool QL, int SD> ...
;     ...
;   finishSM(pB0, pB1, alB, l_reg, pa0, pa1, pa2, pa3); SBAR();
;   pv_d0(o, vb0 + (int)SHM_V, pa0, pa1, pa2, pa3);
;   if (hi == 0) li_l[r32] = l_reg; asm volatile("s_waitcnt vmcnt(0) lgkmcnt(0)" ::: "memory");
; #pragma unroll
;   for (int r = 0; r < 16; ++r) { const float rl = __builtin_amdgcn_rcpf(li_l[crow(r, hi)]);
; #pragma unroll
;     for (int d = 0; d < 4; ++d) o[d][r] *= rl; }
; __device__ __forceinline__ void store_o_bf16(const att::f32x16 (&o)[4], bf16* base  , unsigned char* lds) {
;     const int tid = opaque_tid(), lane = tid & 63, wave = __builtin_amdgcn_readfirstlane(tid >> 6), r32 = lane & 31, hi = lane >> 5;
;     __syncthreads();
;     float* T = (float*)(lds + wave * 16896);
; #pragma unroll
;     for (int r = 0; r < 16; ++r) { float* tp = T + att::crow(r, hi) * 132 + r32;
	v_mfma_f32_32x32x16_bf16 v[2:17], v[80:83], v[84:87], v[2:17]
	ds_read_b64_tr_b16 v[84:85], v151 offset:0x600
	ds_read_b64_tr_b16 v[86:87], v151 offset:0xe00
	v_mfma_f32_32x32x16_bf16 v[2:17], v[76:79], v[88:91], v[2:17]
	ds_read_b64_tr_b16 v[88:89], v151 offset:0x1600
	ds_read_b64_tr_b16 v[90:91], v151 offset:0x1e00
	v_mfma_f32_32x32x16_bf16 v[2:17], v[68:71], v[92:95], v[2:17]
	ds_read_b64_tr_b16 v[92:93], v151 offset:0x2600
	ds_read_b64_tr_b16 v[94:95], v151 offset:0x2e00
	v_mfma_f32_32x32x16_bf16 v[2:17], v[72:75], v[104:107], v[2:17]
	ds_read_b64_tr_b16 v[104:105], v151 offset:0x3600
	ds_read_b64_tr_b16 v[106:107], v151 offset:0x3e00
	s_waitcnt lgkmcnt(0)
	v_mfma_f32_32x32x16_bf16 v[34:49], v[80:83], v[84:87], v[34:49]
	v_mfma_f32_32x32x16_bf16 v[34:49], v[76:79], v[88:91], v[34:49]
	v_mfma_f32_32x32x16_bf16 v[34:49], v[68:71], v[92:95], v[34:49]
	v_mfma_f32_32x32x16_bf16 v[34:49], v[72:75], v[104:107], v[34:49]
	s_and_saveexec_b64 s[2:3], s[0:1]
	v_add_f32_e32 v68, v102, v103
	v_fmac_f32_e32 v68, v150, v130
	v_add_f32_e32 v66, v66, v67
	v_fmac_f32_e32 v66, v68, v98
	ds_write_b32 v149, v66
	s_or_b64 exec, exec, s[2:3]
	s_waitcnt vmcnt(0) lgkmcnt(0)
	v_add_u32_e32 v0, v148, v0
	ds_read_b128 v[66:69], v0
	ds_read_b128 v[70:73], v0 offset:32
	v_readlane_b32 s2, v253, 7
	v_readlane_b32 s3, v253, 8
	s_waitcnt lgkmcnt(1)
	v_rcp_f32_e32 v66, v66
	v_rcp_f32_e32 v67, v67
	v_mul_f32_e32 v75, v66, v2
	v_rcp_f32_e32 v2, v68
	v_mul_f32_e32 v68, v67, v3
	v_rcp_f32_e32 v3, v69
	v_mul_f32_e32 v74, v66, v18
	v_mul_f32_e32 v50, v66, v50
	v_mul_f32_e32 v34, v66, v34
	v_mul_f32_e32 v66, v67, v19
	v_mul_f32_e32 v51, v67, v51
	v_mul_f32_e32 v35, v67, v35
	v_mul_f32_e32 v67, v2, v20
	v_mul_f32_e32 v52, v2, v52
	v_mul_f32_e32 v69, v2, v4
	v_mul_f32_e32 v36, v2, v36
	v_mul_f32_e32 v76, v3, v21
	s_waitcnt lgkmcnt(0)
	v_rcp_f32_e32 v2, v70
	v_mul_f32_e32 v53, v3, v53
	v_mul_f32_e32 v70, v3, v5
	v_mul_f32_e32 v37, v3, v37
	v_rcp_f32_e32 v3, v71
	v_rcp_f32_e32 v18, v72
	v_mul_f32_e32 v22, v2, v22
	v_mul_f32_e32 v54, v2, v54
	v_mul_f32_e32 v6, v2, v6
	v_mul_f32_e32 v38, v2, v38
	v_mul_f32_e32 v23, v3, v23
	v_mul_f32_e32 v55, v3, v55
	v_mul_f32_e32 v7, v3, v7
	v_mul_f32_e32 v39, v3, v39
	v_mul_f32_e32 v24, v18, v24
	v_mul_f32_e32 v56, v18, v56
	ds_read_b128 v[2:5], v0 offset:64
	v_mul_f32_e32 v8, v18, v8
	v_mul_f32_e32 v40, v18, v40
	ds_read_b128 v[18:21], v0 offset:96
	v_rcp_f32_e32 v71, v73
	s_waitcnt lgkmcnt(1)
	v_rcp_f32_e32 v0, v2
	v_rcp_f32_e32 v3, v3
	v_rcp_f32_e32 v4, v4
	v_rcp_f32_e32 v5, v5
	s_waitcnt lgkmcnt(0)
	v_rcp_f32_e32 v18, v18
	v_rcp_f32_e32 v19, v19
	v_rcp_f32_e32 v20, v20
	v_rcp_f32_e32 v21, v21
	v_mul_f32_e32 v2, v71, v57
	v_mul_f32_e32 v26, v0, v26
	v_mul_f32_e32 v57, v0, v58
	v_mul_f32_e32 v10, v0, v10
	v_mul_f32_e32 v0, v0, v42
	v_mul_f32_e32 v27, v3, v27
	v_mul_f32_e32 v42, v3, v59
	v_mul_f32_e32 v11, v3, v11
	v_mul_f32_e32 v3, v3, v43
	v_mul_f32_e32 v28, v4, v28
	v_mul_f32_e32 v43, v4, v60
	v_mul_f32_e32 v12, v4, v12
	v_mul_f32_e32 v4, v4, v44
	v_mul_f32_e32 v29, v5, v29
	v_mul_f32_e32 v44, v5, v61
	v_mul_f32_e32 v13, v5, v13
	v_mul_f32_e32 v5, v5, v45
	v_mul_f32_e32 v30, v18, v30
	v_mul_f32_e32 v45, v18, v62
	v_mul_f32_e32 v14, v18, v14
	v_mul_f32_e32 v18, v18, v46
	v_mul_f32_e32 v31, v19, v31
	v_mul_f32_e32 v46, v19, v63
	v_mul_f32_e32 v15, v19, v15
	v_mul_f32_e32 v19, v19, v47
	v_mul_f32_e32 v32, v20, v32
	v_mul_f32_e32 v47, v20, v64
	v_mul_f32_e32 v16, v20, v16
	v_mul_f32_e32 v20, v20, v48
	v_mul_f32_e32 v33, v21, v33
	v_mul_f32_e32 v48, v21, v65
	v_mul_f32_e32 v17, v21, v17
	v_mul_f32_e32 v21, v21, v49
	v_mov_b32_e32 v49, v188
	s_nop 0
	v_readfirstlane_b32 s0, v49
	s_ashr_i32 s0, s0, 6
	v_lshrrev_b32_e32 v59, 3, v49
	v_and_b32_e32 v58, 31, v49
	s_mul_i32 s1, s0, 0x4200
	v_and_b32_e32 v59, 4, v59
	s_add_i32 s1, s1, 0
	v_lshlrev_b32_e32 v58, 2, v58
	v_mul_u32_u24_e32 v59, 0x210, v59
	v_add3_u32 v58, s1, v58, v59
	s_barrier
; __device__ __forceinline__ int opaque_tid() { int t = threadIdx.x; asm volatile("" : "+v"(t)); return t; }
; __device__ __forceinline__ int crow(int r, int hi) { return (r & 3) + 8 * (r >> 2) + 4 * hi; }
; __device__ __forceinline__ unsigned cvtpk(float lo, float hi) { unsigned r; asm volatile("v_cvt_pk_bf16_f32 %0, %1, %2" : "=v"(r) : "v"(lo), "v"(hi)); return r; }
; __device__ __forceinline__ void store_o_bf16(const att::f32x16 (&o)[4], bf16* base  , unsigned char* lds) {
;     const int tid = opaque_tid(), lane = tid & 63, wave = __builtin_amdgcn_readfirstlane(tid >> 6), r32 = lane & 31, hi = lane >> 5;
;     __syncthreads();
;     float* T = (float*)(lds + wave * 16896);
; #pragma unroll
;     for (int r = 0; r < 16; ++r) { float* tp = T + att::crow(r, hi) * 132 + r32;
; #pragma unroll
;         for (int d = 0; d < 4; ++d) tp[32 * d] = o[d][r]; }
; #pragma unroll
;     for (int k = 0; k < 8; ++k) { const int chunk = k * 64 + lane, row = chunk >> 4, c8 = chunk & 15;
;         const f32x4 a = *(const f32x4*)(T + row * 132 + c8 * 8), b = *(const f32x4*)(T + row * 132 + c8 * 8 + 4);
;         v4u w; w.x = att::cvtpk(a.x, a.y); w.y = att::cvtpk(a.z, a.w); w.z = att::cvtpk(b.x, b.y); w.w = att::cvtpk(b.z, b.w);
;         *(v4u*)(base + (size_t)(wave * 32 + row) * DM + c8 * 8) = w; }
; }
	ds_write2_b32 v58, v74, v50 offset1:32
	ds_write2_b32 v58, v75, v34 offset0:64 offset1:96
	ds_write2_b32 v58, v66, v51 offset0:132 offset1:164
	ds_write2_b32 v58, v68, v35 offset0:196 offset1:228
	v_add_u32_e32 v34, 0x400, v58
	ds_write2_b32 v34, v67, v52 offset0:8 offset1:40
	ds_write2_b32 v34, v69, v36 offset0:72 offset1:104
	ds_write2_b32 v34, v76, v53 offset0:140 offset1:172
	ds_write2_b32 v34, v70, v37 offset0:204 offset1:236
	v_add_u32_e32 v34, 0x1000, v58
	ds_write2_b32 v34, v22, v54 offset0:32 offset1:64
	ds_write2_b32 v34, v6, v38 offset0:96 offset1:128
	ds_write2_b32 v34, v23, v55 offset0:164 offset1:196
	v_add_u32_e32 v6, 0x1200, v58
	ds_write2_b32 v6, v7, v39 offset0:100 offset1:132
	v_add_u32_e32 v6, 0x1400, v58
	v_mul_f32_e32 v25, v71, v25
	v_mul_f32_e32 v9, v71, v9
	v_mul_f32_e32 v41, v71, v41
	ds_write2_b32 v6, v24, v56 offset0:40 offset1:72
	ds_write2_b32 v6, v8, v40 offset0:104 offset1:136
	ds_write2_b32 v6, v25, v2 offset0:172 offset1:204
	v_add_u32_e32 v2, 0x1600, v58
	ds_write2_b32 v2, v9, v41 offset0:108 offset1:140
	v_add_u32_e32 v2, 0x2000, v58
	ds_write2_b32 v2, v26, v57 offset0:64 offset1:96
	ds_write2_b32 v2, v10, v0 offset0:128 offset1:160
	ds_write2_b32 v2, v27, v42 offset0:196 offset1:228
	v_add_u32_e32 v0, 0x2400, v58
	ds_write2_b32 v0, v11, v3 offset0:4 offset1:36
	ds_write2_b32 v0, v28, v43 offset0:72 offset1:104
	ds_write2_b32 v0, v12, v4 offset0:136 offset1:168
	ds_write2_b32 v0, v29, v44 offset0:204 offset1:236
	v_add_u32_e32 v0, 0x2800, v58
	ds_write2_b32 v0, v13, v5 offset0:12 offset1:44
	v_add_u32_e32 v0, 0x3000, v58
	ds_write2_b32 v0, v30, v45 offset0:96 offset1:128
	ds_write2_b32 v0, v14, v18 offset0:160 offset1:192
	v_add_u32_e32 v0, 0x3200, v58
	ds_write2_b32 v0, v31, v46 offset0:100 offset1:132
	v_add_u32_e32 v0, 0x3400, v58
	ds_write2_b32 v0, v15, v19 offset0:36 offset1:68
	ds_write2_b32 v0, v32, v47 offset0:104 offset1:136
	ds_write2_b32 v0, v16, v20 offset0:168 offset1:200
	v_add_u32_e32 v0, 0x3600, v58
	ds_write2_b32 v0, v33, v48 offset0:108 offset1:140
	v_add_u32_e32 v0, 0x3800, v58
	ds_write2_b32 v0, v17, v21 offset0:44 offset1:76
	v_lshlrev_b32_e32 v0, 3, v49
	v_and_b32_e32 v0, 0x78, v0
	v_bfe_u32 v12, v49, 4, 2
	v_lshlrev_b32_e32 v2, 2, v0
	v_mul_u32_u24_e32 v3, 0x210, v12
	v_lshl_or_b32 v18, s0, 5, v12
	v_add3_u32 v22, s1, v2, v3
	v_lshlrev_b32_e32 v0, 1, v0
	v_ashrrev_i32_e32 v19, 31, v18
	ds_read_b128 v[2:5], v22
	ds_read_b128 v[8:11], v22 offset:16
	v_lshl_add_u64 v[16:17], s[2:3], 0, v[0:1]
	v_lshlrev_b64 v[20:21], 12, v[18:19]
	s_waitcnt lgkmcnt(1)
	v_cvt_pk_bf16_f32 v2, v2, v3
	v_cvt_pk_bf16_f32 v3, v4, v5
	s_waitcnt lgkmcnt(0)
	v_cvt_pk_bf16_f32 v4, v8, v9
	v_cvt_pk_bf16_f32 v5, v10, v11
	ds_read_b128 v[8:11], v22 offset:2112
	ds_read_b128 v[12:15], v22 offset:2128
	v_lshl_add_u64 v[20:21], v[16:17], 0, v[20:21]
	global_store_dwordx4 v[20:21], v[2:5], off offset:2048
	v_lshl_add_u64 v[6:7], v[16:17], 0, s[4:5]
	s_waitcnt lgkmcnt(1)
	v_cvt_pk_bf16_f32 v2, v8, v9
	v_cvt_pk_bf16_f32 v3, v10, v11
	s_waitcnt lgkmcnt(0)
	v_cvt_pk_bf16_f32 v4, v12, v13
	v_or_b32_e32 v12, 4, v18
	v_ashrrev_i32_e32 v13, 31, v12
	v_lshlrev_b64 v[20:21], 12, v[12:13]
	v_cvt_pk_bf16_f32 v5, v14, v15
	ds_read_b128 v[8:11], v22 offset:4224
	ds_read_b128 v[12:15], v22 offset:4240
	v_lshl_add_u64 v[20:21], v[16:17], 0, v[20:21]
	global_store_dwordx4 v[20:21], v[2:5], off offset:2048
	s_waitcnt lgkmcnt(1)
	s_nop 0
	v_cvt_pk_bf16_f32 v2, v8, v9
	v_cvt_pk_bf16_f32 v3, v10, v11
	s_waitcnt lgkmcnt(0)
	v_cvt_pk_bf16_f32 v4, v12, v13
	v_or_b32_e32 v12, 8, v18
	v_ashrrev_i32_e32 v13, 31, v12
	v_lshlrev_b64 v[20:21], 12, v[12:13]
	v_cvt_pk_bf16_f32 v5, v14, v15
	ds_read_b128 v[8:11], v22 offset:6336
	ds_read_b128 v[12:15], v22 offset:6352
	v_lshl_add_u64 v[20:21], v[16:17], 0, v[20:21]
	global_store_dwordx4 v[20:21], v[2:5], off offset:2048
	s_waitcnt lgkmcnt(1)
	s_nop 0
	v_cvt_pk_bf16_f32 v2, v8, v9
	v_cvt_pk_bf16_f32 v3, v10, v11
	s_waitcnt lgkmcnt(0)
	v_cvt_pk_bf16_f32 v4, v12, v13
	v_or_b32_e32 v12, 12, v18
	v_ashrrev_i32_e32 v13, 31, v12
	v_lshlrev_b64 v[20:21], 12, v[12:13]
	v_cvt_pk_bf16_f32 v5, v14, v15
	ds_read_b128 v[8:11], v22 offset:8448
	ds_read_b128 v[12:15], v22 offset:8464
	v_lshl_add_u64 v[20:21], v[16:17], 0, v[20:21]
	global_store_dwordx4 v[20:21], v[2:5], off offset:2048
	s_waitcnt lgkmcnt(1)
	s_nop 0
	v_cvt_pk_bf16_f32 v2, v8, v9
	v_cvt_pk_bf16_f32 v3, v10, v11
	s_waitcnt lgkmcnt(0)
	v_cvt_pk_bf16_f32 v4, v12, v13
	v_or_b32_e32 v12, 16, v18
	v_ashrrev_i32_e32 v13, 31, v12
	v_lshlrev_b64 v[20:21], 12, v[12:13]
	v_cvt_pk_bf16_f32 v5, v14, v15
	ds_read_b128 v[8:11], v22 offset:10560
	ds_read_b128 v[12:15], v22 offset:10576
	v_lshl_add_u64 v[20:21], v[16:17], 0, v[20:21]
	global_store_dwordx4 v[20:21], v[2:5], off offset:2048
	s_waitcnt lgkmcnt(1)
	s_nop 0
	v_cvt_pk_bf16_f32 v2, v8, v9
	v_cvt_pk_bf16_f32 v3, v10, v11
	s_waitcnt lgkmcnt(0)
	v_cvt_pk_bf16_f32 v4, v12, v13
	v_or_b32_e32 v12, 20, v18
	v_ashrrev_i32_e32 v13, 31, v12
	v_lshlrev_b64 v[20:21], 12, v[12:13]
	v_cvt_pk_bf16_f32 v5, v14, v15
	ds_read_b128 v[8:11], v22 offset:12672
	ds_read_b128 v[12:15], v22 offset:12688
	v_lshl_add_u64 v[20:21], v[16:17], 0, v[20:21]
	global_store_dwordx4 v[20:21], v[2:5], off offset:2048
	s_waitcnt lgkmcnt(1)
	s_nop 0
	v_cvt_pk_bf16_f32 v2, v8, v9
	v_cvt_pk_bf16_f32 v3, v10, v11
	s_waitcnt lgkmcnt(0)
	v_cvt_pk_bf16_f32 v4, v12, v13
	v_or_b32_e32 v12, 24, v18
	v_ashrrev_i32_e32 v13, 31, v12
	v_lshlrev_b64 v[20:21], 12, v[12:13]
	v_cvt_pk_bf16_f32 v5, v14, v15
	ds_read_b128 v[8:11], v22 offset:14784
	ds_read_b128 v[12:15], v22 offset:14800
	v_lshl_add_u64 v[16:17], v[16:17], 0, v[20:21]
	global_store_dwordx4 v[16:17], v[2:5], off offset:2048
	s_waitcnt lgkmcnt(1)
	s_nop 0
	v_cvt_pk_bf16_f32 v2, v8, v9
	v_or_b32_e32 v8, 28, v18
	v_cvt_pk_bf16_f32 v3, v10, v11
	s_waitcnt lgkmcnt(0)
	v_cvt_pk_bf16_f32 v4, v12, v13
	v_cvt_pk_bf16_f32 v5, v14, v15
	v_mov_b32_e32 v194, 0x3c23d70a
	v_mov_b32_e32 v195, 0x2800
	v_mov_b64_e32 v[196:197], 0x580
